# 4096 weight-conversion tiles moved from phase B side work into the idle tail of the out-proj phase (barrier-free per-wave converter); NCV1=8192
# speedup vs baseline: 1.0104x; 1.0104x over previous
; template <int DK, bool HG, int MODE>
; __device__ void recur_unit(const Params& p, char* smem, int b, int h, char* img, int nstart, int nstep, int nend) {
;     ...
;   const int tid = threadIdx.x, lane = tid & 63, w = tid >> 6, l15 = lane & 15, kg = lane >> 4;
;   const int t = tid & 15, kgp = tid >> 4, k0 = kgp * KPT;
;   const int qcol = HG ? (h * 128) : (2048 + h * 64);
;   const int kcol = HG ? (512 + h * 128) : (2304 + h * 64);
;   const int vcol = HG ? (1024 + h * 128) : (2560 + h * 128);
;   const int gcol = HG ? (1536 + h * 128) : (3088 + h * 128);
;   const int ocol = HG ? (h * 128) : (512 + h * 128);
;   const float* gain = HG ? p.norm_h : p.norm_g;
;   float ba[KPT];
;   if (!HG && MODE == 1) {
;     __syncthreads();
;     for (int i = tid; i < 16 * 64; i += 256) Wa[i] = p.w_a2[(i >> 6) * 256 + h * 64 + (i & 63)];
; #pragma unroll
;     for (int i = 0; i < KPT; i++) ba[i] = p.b_a[h * 64 + k0 + i];
;     __syncthreads();
;   }
;   const float g0 = gain[h * 128 + w * 32 + l15], g1 = gain[h * 128 + w * 32 + 16 + l15];
;   f32x4 S[NKT][2];
; #pragma unroll
;   for (int i = 0; i < NKT; i++) { S[i][0] = f32x4{0, 0, 0, 0}; S[i][1] = f32x4{0, 0, 0, 0}; }
;   float4 pl[4];
;   uint4 pq, pk, pv;
;   u16 psg[8];
;   u32x4 imA[NIM], imB[NIM];
;   u16 psgB[8];
;   auto prefetch = [&](int n, u32x4 (&im)[NIM], u16 (&psg)[8]) {
;     if (MODE == 2) {
;       const char* src = img + (size_t)n * IMG;
; #pragma unroll
;       for (int i = 0; i < NIM; i++) if (tid * 16 + 4096 * i < IMG) im[i] = *(const u32x4*)(src + tid * 16 + 4096 * i);
;       {
;         const u32x4 g = *(const u32x4*)(p.P + ((size_t)b * SEQ + n * 16 + (tid >> 4)) * INC + gcol + (tid & 15) * 8);
;     ...
;   if (MODE == 2) {
;     prefetch(0, imA, psg);
;     prefetch(1, imB, psgB);
;     for (int n = 0; n < SEQ / 16; n += 2) {
;       if (n == 62) mid_barrier(p, smem);
;       step(n, imA, psg); step(n + 1, imB, psgB);
;     }
.Lrec_gla_entry:
	v_readlane_b32 s6, v240, 52
	v_readlane_b32 s2, v240, 24
	v_readlane_b32 s3, v240, 25
	s_nop 3
	s_sub_u32 s28, s6, 32
	s_mul_i32 s26, s28, 0x188000
	s_mul_hi_u32 s27, s28, 0x188000
	s_add_u32 s8, s80, s26
	s_addc_u32 s9, s81, s27
	s_lshr_b32 s26, s6, 2
	s_sub_u32 s26, s26, 8
	s_and_b32 s27, s6, 3
	s_mul_i32 s28, s26, 0xe10000
	s_add_u32 s10, s88, s28
	s_addc_u32 s11, s89, 0
	s_lshl_b32 s28, s27, 8
	s_add_u32 s28, s28, 0x1820
	s_add_u32 s10, s10, s28
	s_addc_u32 s11, s11, 0
	s_lshl_b32 s28, s26, 22
	s_add_u32 s12, s2, s28
	s_addc_u32 s13, s3, 0
	s_lshl_b32 s28, s27, 8
	s_add_u32 s28, s28, 0x400
	s_add_u32 s12, s12, s28
	s_addc_u32 s13, s13, 0
	s_sub_u32 s12, s12, 0x10000
	s_subb_u32 s13, s13, 0
	s_mov_b32 s30, 0x3c000000
	s_mov_b32 s4, 1
	s_mov_b32 s36, 0
	v_and_b32_e32 v137, 15, v128
	v_bfe_u32 v139, v128, 4, 2
	v_lshrrev_b32_e32 v142, 6, v128
	v_lshrrev_b32_e32 v178, 4, v128
	v_mul_u32_u24_e32 v202, 144, v137
	v_lshl_add_u32 v144, v139, 3, v202
	v_lshl_add_u32 v202, v142, 5, v137
	v_mul_u32_u24_e32 v202, 40, v202
	v_lshl_add_u32 v145, v139, 3, v202
	v_mul_u32_u24_e32 v202, 40, v137
	v_lshl_add_u32 v146, v139, 3, v202
	v_lshlrev_b32_e32 v147, 4, v139
	v_lshl_add_u32 v148, v142, 6, v147
	v_mul_u32_u24_e32 v202, 0x840, v139
	v_lshl_add_u32 v202, v142, 7, v202
	v_lshl_add_u32 v149, v137, 2, v202
	v_mul_u32_u24_e32 v202, 0x210, v178
	v_lshl_add_u32 v150, v137, 5, v202
	v_lshlrev_b32_e32 v151, 4, v128
	v_add_u32_e32 v152, 0x0, v151
	v_add_u32_e32 v153, 0x1000, v151
	v_add_u32_e32 v154, 0x2000, v151
	v_add_u32_e32 v172, 0x3000, v151
	s_movk_i32 s28, 16
	v_cmp_gt_u32_e64 s[24:25], s28, v128
	s_nop 1
	v_cndmask_b32_e64 v172, 0, v172, s[24:25]
	v_mul_u32_u24_e32 v202, 0x1c20, v178
	v_lshl_add_u32 v173, v137, 4, v202
	v_lshlrev_b32_e32 v202, 11, v178
	v_lshl_add_u32 v174, v137, 4, v202
	v_lshl_add_u32 v202, v142, 5, v137
	s_lshl_b32 s28, s27, 7
	v_add_lshl_u32 v202, s28, v202, 2
	global_load_dword v175, v202, s[64:65]
	global_load_dword v176, v202, s[64:65] offset:64
	v_lshlrev_b32_e32 v203, 2, v139
	v_cmp_gt_u32_e64 s[14:15], v203, v137
	v_add_u32_e32 v184, 1, v203
	v_cmp_gt_u32_e64 s[16:17], v184, v137
	v_add_u32_e32 v184, 2, v203
	v_cmp_gt_u32_e64 s[18:19], v184, v137
	v_add_u32_e32 v184, 3, v203
	v_cmp_gt_u32_e64 s[20:21], v184, v137
	v_cmp_eq_u32_e64 s[22:23], 0, v137
	v_mov_b32_e32 v177, 0x3727c5ac
	v_mov_b32_e32 v48, 0
	v_mov_b32_e32 v49, 0
	v_mov_b32_e32 v50, 0
	v_mov_b32_e32 v51, 0
	v_mov_b32_e32 v52, 0
	v_mov_b32_e32 v53, 0
	v_mov_b32_e32 v54, 0
	v_mov_b32_e32 v55, 0
	v_mov_b32_e32 v56, 0
	v_mov_b32_e32 v57, 0
	v_mov_b32_e32 v58, 0
	v_mov_b32_e32 v59, 0
	v_mov_b32_e32 v60, 0
	v_mov_b32_e32 v61, 0
	v_mov_b32_e32 v62, 0
	v_mov_b32_e32 v63, 0
	v_mov_b32_e32 v64, 0
	v_mov_b32_e32 v65, 0
	v_mov_b32_e32 v66, 0
	v_mov_b32_e32 v67, 0
	v_mov_b32_e32 v68, 0
	v_mov_b32_e32 v69, 0
	v_mov_b32_e32 v70, 0
	v_mov_b32_e32 v71, 0
	v_mov_b32_e32 v72, 0
	v_mov_b32_e32 v73, 0
	v_mov_b32_e32 v74, 0
	v_mov_b32_e32 v75, 0
	v_mov_b32_e32 v76, 0
	v_mov_b32_e32 v77, 0
	v_mov_b32_e32 v78, 0
	v_mov_b32_e32 v79, 0
	global_load_dwordx4 v[0:3], v152, s[8:9]
	global_load_dwordx4 v[4:7], v153, s[8:9]
	global_load_dwordx4 v[8:11], v154, s[8:9]
	global_load_dwordx4 v[12:15], v172, s[8:9]
	s_add_u32 s8, s8, 0x3100
	s_addc_u32 s9, s9, 0
	global_load_dwordx4 v[20:23], v152, s[8:9]
	global_load_dwordx4 v[24:27], v153, s[8:9]
	global_load_dwordx4 v[28:31], v154, s[8:9]
	global_load_dwordx4 v[32:35], v172, s[8:9]
	s_add_u32 s8, s8, 0x3100
	s_addc_u32 s9, s9, 0
	s_waitcnt vmcnt(4)
	ds_write_b128 v151, v[0:3] offset:0
	ds_write_b128 v151, v[4:7] offset:4096
	ds_write_b128 v151, v[8:11] offset:8192
	s_mov_b64 s[26:27], exec
	s_and_b64 exec, exec, s[24:25]
	ds_write_b128 v151, v[12:15] offset:12288
	s_mov_b64 exec, s[26:27]
	global_load_dwordx4 v[0:3], v152, s[8:9]
	global_load_dwordx4 v[4:7], v153, s[8:9]
	global_load_dwordx4 v[8:11], v154, s[8:9]
	global_load_dwordx4 v[12:15], v172, s[8:9]
	s_add_u32 s8, s8, 0x3100
	s_addc_u32 s9, s9, 0
	s_waitcnt lgkmcnt(0)
	.p2align 3
	s_nop 0

; template <int DK, bool HG, int MODE>
; __device__ void recur_unit(const Params& p, char* smem, int b, int h, char* img, int nstart, int nstep, int nend) {
;     ...
;     f32x4 sc = f32x4{0, 0, 0, 0};
;     bf16x8 qf[NKS];
; #pragma unroll
;     for (int st = 0; st < NKS; st++) {
;       bf16x4 q0 = *(const bf16x4*)&Qt[l15 * LQ + 32 * st + kg * 4];
;     ...
; #pragma unroll
;     for (int vt = 0; vt < 2; vt++) {
;       o[vt] = __builtin_amdgcn_mfma_f32_16x16x16bf16_1k(pA, vf[vt], f32x4{0, 0, 0, 0}, 0, 0, 0);
;       oin[vt] = f32x4{0, 0, 0, 0};
; #pragma unroll
;       for (int st = 0; st < NKS; st++) oin[vt] = __builtin_amdgcn_mfma_f32_16x16x32_bf16(qf[st], sbv[vt][st], oin[vt], 0, 0, 0);
;     }
;     STAGE();
;     bf16x4 khf[NKT];
; #pragma unroll
;     for (int kt2 = 0; kt2 < NKT; kt2++) {
;       khf[kt2] = *(const bf16x4*)&KhT[(16 * kt2 + l15) * 20 + kg * 4];
;       float4 g4 = *(const float4*)&Gch[16 * kt2 + kg * 4];
;       f32x4 gv = f32x4{g4.x, g4.y, g4.z, g4.w};
;       S[kt2][0] *= gv; S[kt2][1] *= gv;
;     }
;     STAGE();
; #pragma unroll
;     for (int kt2 = 0; kt2 < NKT; kt2++) {
; #pragma unroll
;       for (int vt = 0; vt < 2; vt++)
;         S[kt2][vt] = __builtin_amdgcn_mfma_f32_16x16x16bf16_1k(khf[kt2], vf[vt], S[kt2][vt], 0, 0, 0);
;     }
;     STAGE();
;     float ss[4];
; #pragma unroll
;     for (int r = 0; r < 4; r++) {
;       o[0][r] += oin[0][r]; o[1][r] += oin[1][r];
;       float s = o[0][r] * o[0][r] + o[1][r] * o[1][r];
;       s = dpp_row_sum(s);
;       ss[r] = s;
;     }
;     if (l15 == 0) *(float4*)&SS[w * 16 + kg * 4] = make_float4(ss[0], ss[1], ss[2], ss[3]);
;     __syncthreads();
;     {
;       float4 a0 = *(const float4*)&SS[0 * 16 + kg * 4], a1 = *(const float4*)&SS[1 * 16 + kg * 4];
;       float4 a2 = *(const float4*)&SS[2 * 16 + kg * 4], a3 = *(const float4*)&SS[3 * 16 + kg * 4];
;       float tot[4] = {a0.x + a1.x + a2.x + a3.x, a0.y + a1.y + a2.y + a3.y, a0.z + a1.z + a2.z + a3.z, a0.w + a1.w + a2.w + a3.w};
; #pragma unroll
;       for (int r = 0; r < 4; r++) {
;         const float rstd = rsqrtf(tot[r] * (1.f / 128.f) + LN_EPS);
;         const int li = (kg * 4 + r) * 136 + w * 32 + l15;
;         sgate[r] = bf2f(GT[li]); sgate[4 + r] = bf2f(GT[li + 16]);
;         OT[li] = f2bf(o[0][r] * rstd * g0 * sgate[r]);
;         OT[li + 16] = f2bf(o[1][r] * rstd * g1 * sgate[4 + r]);
;       }
.Lrec_gla_p0_nost:
	global_load_dwordx4 v[40:43], v173, s[10:11]
	s_add_u32 s10, s10, 0x1c200
	s_addc_u32 s11, s11, 0
	s_add_u32 s12, s12, 0x8000
	s_addc_u32 s13, s13, 0
	ds_read_b64 v[224:225], v144 offset:2368
	ds_read_b64 v[226:227], v144 offset:2400
	ds_read_b64 v[228:229], v144 offset:64
	ds_read_b64 v[230:231], v144 offset:96
	ds_read_b64 v[232:233], v146 offset:5888
	ds_read_b64 v[234:235], v146 offset:6528
	ds_read_b128 v[236:239], v147 offset:12416
	ds_read_b128 v[112:115], v147 offset:12480
	s_waitcnt lgkmcnt(14)
	v_mfma_f32_16x16x32_bf16 a[0:3], v[204:207], v[208:211], 0
	v_mfma_f32_16x16x32_bf16 a[4:7], v[208:211], v[120:123], 0
	v_mfma_f32_16x16x32_bf16 a[8:11], v[208:211], v[156:159], 0
	s_waitcnt lgkmcnt(8)
	v_pk_mul_f32 v[48:49], v[48:49], v[216:217]
	v_pk_mul_f32 v[50:51], v[50:51], v[218:219]
	v_pk_mul_f32 v[52:53], v[52:53], v[216:217]
	v_pk_mul_f32 v[54:55], v[54:55], v[218:219]
	v_mfma_f32_16x16x16_bf16 v[48:51], v[212:213], v[116:117], v[48:51]
	v_pk_mul_f32 v[56:57], v[56:57], v[220:221]
	v_pk_mul_f32 v[58:59], v[58:59], v[222:223]
	v_mfma_f32_16x16x16_bf16 v[52:55], v[212:213], v[118:119], v[52:55]
	v_pk_mul_f32 v[60:61], v[60:61], v[220:221]
	v_pk_mul_f32 v[62:63], v[62:63], v[222:223]
	v_mfma_f32_16x16x16_bf16 v[56:59], v[214:215], v[116:117], v[56:59]
	v_cvt_pk_bf16_f32 v120, v64, v65
	v_cvt_pk_bf16_f32 v121, v66, v67
	v_mfma_f32_16x16x16_bf16 v[60:63], v[214:215], v[118:119], v[60:63]
	v_cvt_pk_bf16_f32 v122, v72, v73
	v_cvt_pk_bf16_f32 v123, v74, v75
	v_cvt_pk_bf16_f32 v156, v68, v69
	v_cvt_pk_bf16_f32 v157, v70, v71
	v_cvt_pk_bf16_f32 v158, v76, v77
	v_cvt_pk_bf16_f32 v159, v78, v79
	s_waitcnt lgkmcnt(4)
	v_mfma_f32_16x16x32_bf16 a[0:3], v[224:227], v[228:231], a[0:3]
	v_mfma_f32_16x16x32_bf16 a[4:7], v[228:231], v[120:123], a[4:7]
	v_mfma_f32_16x16x32_bf16 a[8:11], v[228:231], v[156:159], a[8:11]
	s_waitcnt lgkmcnt(0)
	v_pk_mul_f32 v[64:65], v[64:65], v[236:237]
	v_pk_mul_f32 v[66:67], v[66:67], v[238:239]
	v_pk_mul_f32 v[68:69], v[68:69], v[236:237]
	v_pk_mul_f32 v[70:71], v[70:71], v[238:239]
	v_mfma_f32_16x16x16_bf16 v[64:67], v[232:233], v[116:117], v[64:67]
	v_pk_mul_f32 v[72:73], v[72:73], v[112:113]
	v_pk_mul_f32 v[74:75], v[74:75], v[114:115]
	v_mfma_f32_16x16x16_bf16 v[68:71], v[232:233], v[118:119], v[68:71]
	v_pk_mul_f32 v[76:77], v[76:77], v[112:113]
	v_pk_mul_f32 v[78:79], v[78:79], v[114:115]
	v_mfma_f32_16x16x16_bf16 v[72:75], v[234:235], v[116:117], v[72:75]
	s_nop 1
	v_mfma_f32_16x16x16_bf16 v[76:79], v[234:235], v[118:119], v[76:79]
	ds_read_b128 v[204:207], v147 offset:39168
	ds_read_b128 v[208:211], v147 offset:39232
	ds_read_b128 v[212:215], v147 offset:39296
	ds_read_b128 v[216:219], v147 offset:39360
	v_accvgpr_read_b32 v224, a0
	v_accvgpr_read_b32 v225, a1
	v_accvgpr_read_b32 v226, a2
	v_accvgpr_read_b32 v227, a3
	v_cndmask_b32_e64 v224, v224, 0, s[14:15]
	v_cndmask_b32_e64 v225, v225, 0, s[16:17]
	v_cndmask_b32_e64 v226, v226, 0, s[18:19]
	v_cndmask_b32_e64 v227, v227, 0, s[20:21]
	v_cvt_pk_bf16_f32 v140, v224, v225
	v_cvt_pk_bf16_f32 v141, v226, v227
	s_nop 1
	v_mfma_f32_16x16x16_bf16 v[186:189], v[140:141], v[116:117], 0
	v_mfma_f32_16x16x16_bf16 v[190:193], v[140:141], v[118:119], 0
	v_accvgpr_read_b32 v228, a4
	v_accvgpr_read_b32 v229, a5
	v_accvgpr_read_b32 v230, a6
	v_accvgpr_read_b32 v231, a7
	v_accvgpr_read_b32 v232, a8
	v_accvgpr_read_b32 v233, a9
	v_accvgpr_read_b32 v234, a10
	v_accvgpr_read_b32 v235, a11
	s_nop 1
	v_pk_add_f32 v[186:187], v[186:187], v[228:229]
	v_pk_add_f32 v[188:189], v[188:189], v[230:231]
	v_pk_add_f32 v[190:191], v[190:191], v[232:233]
	v_pk_add_f32 v[192:193], v[192:193], v[234:235]
	v_pk_mul_f32 v[236:237], v[190:191], v[190:191]
	v_pk_mul_f32 v[238:239], v[192:193], v[192:193]
	v_pk_fma_f32 v[112:113], v[186:187], v[186:187], v[236:237]
	v_pk_fma_f32 v[114:115], v[188:189], v[188:189], v[238:239]
	s_nop 1
	v_add_f32_dpp v112, v112, v112 row_ror:8 row_mask:0xf bank_mask:0xf
	v_add_f32_dpp v113, v113, v113 row_ror:8 row_mask:0xf bank_mask:0xf
	v_add_f32_dpp v114, v114, v114 row_ror:8 row_mask:0xf bank_mask:0xf
	v_add_f32_dpp v115, v115, v115 row_ror:8 row_mask:0xf bank_mask:0xf
	v_add_f32_dpp v112, v112, v112 row_ror:4 row_mask:0xf bank_mask:0xf
	v_add_f32_dpp v113, v113, v113 row_ror:4 row_mask:0xf bank_mask:0xf
	v_add_f32_dpp v114, v114, v114 row_ror:4 row_mask:0xf bank_mask:0xf
	v_add_f32_dpp v115, v115, v115 row_ror:4 row_mask:0xf bank_mask:0xf
	v_add_f32_dpp v112, v112, v112 row_ror:2 row_mask:0xf bank_mask:0xf
	v_add_f32_dpp v113, v113, v113 row_ror:2 row_mask:0xf bank_mask:0xf
	v_add_f32_dpp v114, v114, v114 row_ror:2 row_mask:0xf bank_mask:0xf
	v_add_f32_dpp v115, v115, v115 row_ror:2 row_mask:0xf bank_mask:0xf
	v_add_f32_dpp v112, v112, v112 row_ror:1 row_mask:0xf bank_mask:0xf
	v_add_f32_dpp v113, v113, v113 row_ror:1 row_mask:0xf bank_mask:0xf
	v_add_f32_dpp v114, v114, v114 row_ror:1 row_mask:0xf bank_mask:0xf
	v_add_f32_dpp v115, v115, v115 row_ror:1 row_mask:0xf bank_mask:0xf
	s_mov_b64 s[26:27], exec
	s_and_b64 exec, exec, s[22:23]
	ds_write_b128 v148, v[112:115] offset:38912
	s_mov_b64 exec, s[26:27]
	s_waitcnt lgkmcnt(1)
	v_pk_add_f32 v[220:221], v[204:205], v[208:209]
	v_pk_add_f32 v[222:223], v[206:207], v[210:211]
	v_pk_add_f32 v[220:221], v[220:221], v[212:213]
	v_pk_add_f32 v[222:223], v[222:223], v[214:215]
	v_pk_add_f32 v[220:221], v[220:221], v[216:217]
	v_pk_add_f32 v[222:223], v[222:223], v[218:219]
	v_fma_f32 v220, v220, s30, v177
	v_fma_f32 v221, v221, s30, v177
	v_fma_f32 v222, v222, s30, v177
	v_fma_f32 v223, v223, s30, v177
	v_rsq_f32_e32 v220, v220
	v_rsq_f32_e32 v221, v221
	v_rsq_f32_e32 v222, v222
	v_rsq_f32_e32 v223, v223
	s_nop 0
	v_mul_f32_e32 v204, v194, v220
	v_mul_f32_e32 v205, v195, v221
	v_mul_f32_e32 v206, v196, v222
	v_mul_f32_e32 v207, v197, v223
	v_mul_f32_e32 v208, v198, v220
	v_mul_f32_e32 v209, v199, v221
	v_mul_f32_e32 v210, v200, v222
	v_mul_f32_e32 v211, v201, v223
	v_mul_f32_e32 v204, v175, v204
	v_mul_f32_e32 v205, v175, v205
	v_mul_f32_e32 v206, v175, v206
	v_mul_f32_e32 v207, v175, v207
	v_mul_f32_e32 v208, v176, v208
	v_mul_f32_e32 v209, v176, v209
	v_mul_f32_e32 v210, v176, v210
	v_mul_f32_e32 v211, v176, v211
	ds_write_b32 v149, v204 offset:47872
	ds_write_b32 v149, v205 offset:48400
	ds_write_b32 v149, v206 offset:48928
	ds_write_b32 v149, v207 offset:49456
	ds_write_b32 v149, v208 offset:47936
	ds_write_b32 v149, v209 offset:48464
	ds_write_b32 v149, v210 offset:48992
	ds_write_b32 v149, v211 offset:49520
	s_cmp_lg_u32 s29, 0
	s_cbranch_scc1 .Lrec_gla_p0w_d
	s_waitcnt vmcnt(8)
	s_branch .Lrec_gla_p0w_c

; template <int DK, bool HG, int MODE>
; __device__ void recur_unit(const Params& p, char* smem, int b, int h, char* img, int nstart, int nstep, int nend) {
;     ...
;     f32x4 sc = f32x4{0, 0, 0, 0};
;     bf16x8 qf[NKS];
; #pragma unroll
;     for (int st = 0; st < NKS; st++) {
;       bf16x4 q0 = *(const bf16x4*)&Qt[l15 * LQ + 32 * st + kg * 4];
;     ...
; #pragma unroll
;     for (int vt = 0; vt < 2; vt++) {
;       o[vt] = __builtin_amdgcn_mfma_f32_16x16x16bf16_1k(pA, vf[vt], f32x4{0, 0, 0, 0}, 0, 0, 0);
;       oin[vt] = f32x4{0, 0, 0, 0};
; #pragma unroll
;       for (int st = 0; st < NKS; st++) oin[vt] = __builtin_amdgcn_mfma_f32_16x16x32_bf16(qf[st], sbv[vt][st], oin[vt], 0, 0, 0);
;     }
;     STAGE();
;     bf16x4 khf[NKT];
; #pragma unroll
;     for (int kt2 = 0; kt2 < NKT; kt2++) {
;       khf[kt2] = *(const bf16x4*)&KhT[(16 * kt2 + l15) * 20 + kg * 4];
;       float4 g4 = *(const float4*)&Gch[16 * kt2 + kg * 4];
;       f32x4 gv = f32x4{g4.x, g4.y, g4.z, g4.w};
;       S[kt2][0] *= gv; S[kt2][1] *= gv;
;     }
;     STAGE();
; #pragma unroll
;     for (int kt2 = 0; kt2 < NKT; kt2++) {
; #pragma unroll
;       for (int vt = 0; vt < 2; vt++)
;         S[kt2][vt] = __builtin_amdgcn_mfma_f32_16x16x16bf16_1k(khf[kt2], vf[vt], S[kt2][vt], 0, 0, 0);
;     }
;     STAGE();
;     float ss[4];
; #pragma unroll
;     for (int r = 0; r < 4; r++) {
;       o[0][r] += oin[0][r]; o[1][r] += oin[1][r];
;       float s = o[0][r] * o[0][r] + o[1][r] * o[1][r];
;       s = dpp_row_sum(s);
;       ss[r] = s;
;     }
;     if (l15 == 0) *(float4*)&SS[w * 16 + kg * 4] = make_float4(ss[0], ss[1], ss[2], ss[3]);
;     __syncthreads();
;     {
;       float4 a0 = *(const float4*)&SS[0 * 16 + kg * 4], a1 = *(const float4*)&SS[1 * 16 + kg * 4];
;       float4 a2 = *(const float4*)&SS[2 * 16 + kg * 4], a3 = *(const float4*)&SS[3 * 16 + kg * 4];
;       float tot[4] = {a0.x + a1.x + a2.x + a3.x, a0.y + a1.y + a2.y + a3.y, a0.z + a1.z + a2.z + a3.z, a0.w + a1.w + a2.w + a3.w};
; #pragma unroll
;       for (int r = 0; r < 4; r++) {
;         const float rstd = rsqrtf(tot[r] * (1.f / 128.f) + LN_EPS);
;         const int li = (kg * 4 + r) * 136 + w * 32 + l15;
;         sgate[r] = bf2f(GT[li]); sgate[4 + r] = bf2f(GT[li + 16]);
;         OT[li] = f2bf(o[0][r] * rstd * g0 * sgate[r]);
;         OT[li + 16] = f2bf(o[1][r] * rstd * g1 * sgate[4 + r]);
;       }
.Lrec_gla_p1_nost:
	global_load_dwordx4 v[44:47], v173, s[10:11]
	s_add_u32 s10, s10, 0x1c200
	s_addc_u32 s11, s11, 0
	s_add_u32 s12, s12, 0x8000
	s_addc_u32 s13, s13, 0
	ds_read_b64 v[224:225], v144 offset:14912
	ds_read_b64 v[226:227], v144 offset:14944
	ds_read_b64 v[228:229], v144 offset:12608
	ds_read_b64 v[230:231], v144 offset:12640
	ds_read_b64 v[232:233], v146 offset:18432
	ds_read_b64 v[234:235], v146 offset:19072
	ds_read_b128 v[236:239], v147 offset:24960
	ds_read_b128 v[112:115], v147 offset:25024
	s_waitcnt lgkmcnt(14)
	v_mfma_f32_16x16x32_bf16 a[0:3], v[204:207], v[208:211], 0
	v_mfma_f32_16x16x32_bf16 a[4:7], v[208:211], v[120:123], 0
	v_mfma_f32_16x16x32_bf16 a[8:11], v[208:211], v[156:159], 0
	s_waitcnt lgkmcnt(8)
	v_pk_mul_f32 v[48:49], v[48:49], v[216:217]
	v_pk_mul_f32 v[50:51], v[50:51], v[218:219]
	v_pk_mul_f32 v[52:53], v[52:53], v[216:217]
	v_pk_mul_f32 v[54:55], v[54:55], v[218:219]
	v_mfma_f32_16x16x16_bf16 v[48:51], v[212:213], v[116:117], v[48:51]
	v_pk_mul_f32 v[56:57], v[56:57], v[220:221]
	v_pk_mul_f32 v[58:59], v[58:59], v[222:223]
	v_mfma_f32_16x16x16_bf16 v[52:55], v[212:213], v[118:119], v[52:55]
	v_pk_mul_f32 v[60:61], v[60:61], v[220:221]
	v_pk_mul_f32 v[62:63], v[62:63], v[222:223]
	v_mfma_f32_16x16x16_bf16 v[56:59], v[214:215], v[116:117], v[56:59]
	v_cvt_pk_bf16_f32 v120, v64, v65
	v_cvt_pk_bf16_f32 v121, v66, v67
	v_mfma_f32_16x16x16_bf16 v[60:63], v[214:215], v[118:119], v[60:63]
	v_cvt_pk_bf16_f32 v122, v72, v73
	v_cvt_pk_bf16_f32 v123, v74, v75
	v_cvt_pk_bf16_f32 v156, v68, v69
	v_cvt_pk_bf16_f32 v157, v70, v71
	v_cvt_pk_bf16_f32 v158, v76, v77
	v_cvt_pk_bf16_f32 v159, v78, v79
	s_waitcnt lgkmcnt(4)
	v_mfma_f32_16x16x32_bf16 a[0:3], v[224:227], v[228:231], a[0:3]
	v_mfma_f32_16x16x32_bf16 a[4:7], v[228:231], v[120:123], a[4:7]
	v_mfma_f32_16x16x32_bf16 a[8:11], v[228:231], v[156:159], a[8:11]
	s_waitcnt lgkmcnt(0)
	v_pk_mul_f32 v[64:65], v[64:65], v[236:237]
	v_pk_mul_f32 v[66:67], v[66:67], v[238:239]
	v_pk_mul_f32 v[68:69], v[68:69], v[236:237]
	v_pk_mul_f32 v[70:71], v[70:71], v[238:239]
	v_mfma_f32_16x16x16_bf16 v[64:67], v[232:233], v[116:117], v[64:67]
	v_pk_mul_f32 v[72:73], v[72:73], v[112:113]
	v_pk_mul_f32 v[74:75], v[74:75], v[114:115]
	v_mfma_f32_16x16x16_bf16 v[68:71], v[232:233], v[118:119], v[68:71]
	v_pk_mul_f32 v[76:77], v[76:77], v[112:113]
	v_pk_mul_f32 v[78:79], v[78:79], v[114:115]
	v_mfma_f32_16x16x16_bf16 v[72:75], v[234:235], v[116:117], v[72:75]
	s_nop 1
	v_mfma_f32_16x16x16_bf16 v[76:79], v[234:235], v[118:119], v[76:79]
	ds_read_b128 v[204:207], v147 offset:38912
	ds_read_b128 v[208:211], v147 offset:38976
	ds_read_b128 v[212:215], v147 offset:39040
	ds_read_b128 v[216:219], v147 offset:39104
	v_accvgpr_read_b32 v224, a0
	v_accvgpr_read_b32 v225, a1
	v_accvgpr_read_b32 v226, a2
	v_accvgpr_read_b32 v227, a3
	v_cndmask_b32_e64 v224, v224, 0, s[14:15]
	v_cndmask_b32_e64 v225, v225, 0, s[16:17]
	v_cndmask_b32_e64 v226, v226, 0, s[18:19]
	v_cndmask_b32_e64 v227, v227, 0, s[20:21]
	v_cvt_pk_bf16_f32 v140, v224, v225
	v_cvt_pk_bf16_f32 v141, v226, v227
	s_nop 1
	v_mfma_f32_16x16x16_bf16 v[194:197], v[140:141], v[116:117], 0
	v_mfma_f32_16x16x16_bf16 v[198:201], v[140:141], v[118:119], 0
	v_accvgpr_read_b32 v228, a4
	v_accvgpr_read_b32 v229, a5
	v_accvgpr_read_b32 v230, a6
	v_accvgpr_read_b32 v231, a7
	v_accvgpr_read_b32 v232, a8
	v_accvgpr_read_b32 v233, a9
	v_accvgpr_read_b32 v234, a10
	v_accvgpr_read_b32 v235, a11
	s_nop 1
	v_pk_add_f32 v[194:195], v[194:195], v[228:229]
	v_pk_add_f32 v[196:197], v[196:197], v[230:231]
	v_pk_add_f32 v[198:199], v[198:199], v[232:233]
	v_pk_add_f32 v[200:201], v[200:201], v[234:235]
	v_pk_mul_f32 v[236:237], v[198:199], v[198:199]
	v_pk_mul_f32 v[238:239], v[200:201], v[200:201]
	v_pk_fma_f32 v[112:113], v[194:195], v[194:195], v[236:237]
	v_pk_fma_f32 v[114:115], v[196:197], v[196:197], v[238:239]
	s_nop 1
	v_add_f32_dpp v112, v112, v112 row_ror:8 row_mask:0xf bank_mask:0xf
	v_add_f32_dpp v113, v113, v113 row_ror:8 row_mask:0xf bank_mask:0xf
	v_add_f32_dpp v114, v114, v114 row_ror:8 row_mask:0xf bank_mask:0xf
	v_add_f32_dpp v115, v115, v115 row_ror:8 row_mask:0xf bank_mask:0xf
	v_add_f32_dpp v112, v112, v112 row_ror:4 row_mask:0xf bank_mask:0xf
	v_add_f32_dpp v113, v113, v113 row_ror:4 row_mask:0xf bank_mask:0xf
	v_add_f32_dpp v114, v114, v114 row_ror:4 row_mask:0xf bank_mask:0xf
	v_add_f32_dpp v115, v115, v115 row_ror:4 row_mask:0xf bank_mask:0xf
	v_add_f32_dpp v112, v112, v112 row_ror:2 row_mask:0xf bank_mask:0xf
	v_add_f32_dpp v113, v113, v113 row_ror:2 row_mask:0xf bank_mask:0xf
	v_add_f32_dpp v114, v114, v114 row_ror:2 row_mask:0xf bank_mask:0xf
	v_add_f32_dpp v115, v115, v115 row_ror:2 row_mask:0xf bank_mask:0xf
	v_add_f32_dpp v112, v112, v112 row_ror:1 row_mask:0xf bank_mask:0xf
	v_add_f32_dpp v113, v113, v113 row_ror:1 row_mask:0xf bank_mask:0xf
	v_add_f32_dpp v114, v114, v114 row_ror:1 row_mask:0xf bank_mask:0xf
	v_add_f32_dpp v115, v115, v115 row_ror:1 row_mask:0xf bank_mask:0xf
	s_mov_b64 s[26:27], exec
	s_and_b64 exec, exec, s[22:23]
	ds_write_b128 v148, v[112:115] offset:39168
	s_mov_b64 exec, s[26:27]
	s_waitcnt lgkmcnt(1)
	v_pk_add_f32 v[220:221], v[204:205], v[208:209]
	v_pk_add_f32 v[222:223], v[206:207], v[210:211]
	v_pk_add_f32 v[220:221], v[220:221], v[212:213]
	v_pk_add_f32 v[222:223], v[222:223], v[214:215]
	v_pk_add_f32 v[220:221], v[220:221], v[216:217]
	v_pk_add_f32 v[222:223], v[222:223], v[218:219]
	v_fma_f32 v220, v220, s30, v177
	v_fma_f32 v221, v221, s30, v177
	v_fma_f32 v222, v222, s30, v177
	v_fma_f32 v223, v223, s30, v177
	v_rsq_f32_e32 v220, v220
	v_rsq_f32_e32 v221, v221
	v_rsq_f32_e32 v222, v222
	v_rsq_f32_e32 v223, v223
	s_nop 0
	v_mul_f32_e32 v204, v186, v220
	v_mul_f32_e32 v205, v187, v221
	v_mul_f32_e32 v206, v188, v222
	v_mul_f32_e32 v207, v189, v223
	v_mul_f32_e32 v208, v190, v220
	v_mul_f32_e32 v209, v191, v221
	v_mul_f32_e32 v210, v192, v222
	v_mul_f32_e32 v211, v193, v223
	v_mul_f32_e32 v204, v175, v204
	v_mul_f32_e32 v205, v175, v205
	v_mul_f32_e32 v206, v175, v206
	v_mul_f32_e32 v207, v175, v207
	v_mul_f32_e32 v208, v176, v208
	v_mul_f32_e32 v209, v176, v209
	v_mul_f32_e32 v210, v176, v210
	v_mul_f32_e32 v211, v176, v211
	ds_write_b32 v149, v204 offset:39424
	ds_write_b32 v149, v205 offset:39952
	ds_write_b32 v149, v206 offset:40480
	ds_write_b32 v149, v207 offset:41008
	ds_write_b32 v149, v208 offset:39488
	ds_write_b32 v149, v209 offset:40016
	ds_write_b32 v149, v210 offset:40544
	ds_write_b32 v149, v211 offset:41072
	s_cmp_lg_u32 s29, 0
	s_cbranch_scc1 .Lrec_gla_p1w_d
	s_waitcnt vmcnt(8)
	s_branch .Lrec_gla_p1w_c

; __device__ __forceinline__ float bf2f(u16 v) { return __uint_as_float(((unsigned)v) << 16); }
; template <int DK, bool HG, int MODE>
; __device__ void recur_unit(const Params& p, char* smem, int b, int h, char* img, int nstart, int nstep, int nend) {
;     ...
;     __syncthreads();
;     {
;       float4 a0 = *(const float4*)&SS[0 * 16 + kg * 4], a1 = *(const float4*)&SS[1 * 16 + kg * 4];
;       float4 a2 = *(const float4*)&SS[2 * 16 + kg * 4], a3 = *(const float4*)&SS[3 * 16 + kg * 4];
;       float tot[4] = {a0.x + a1.x + a2.x + a3.x, a0.y + a1.y + a2.y + a3.y, a0.z + a1.z + a2.z + a3.z, a0.w + a1.w + a2.w + a3.w};
; #pragma unroll
;       for (int r = 0; r < 4; r++) {
;         const float rstd = rsqrtf(tot[r] * (1.f / 128.f) + LN_EPS);
;         const int li = (kg * 4 + r) * 136 + w * 32 + l15;
;         sgate[r] = bf2f(GT[li]); sgate[4 + r] = bf2f(GT[li + 16]);
;         OT[li] = f2bf(o[0][r] * rstd * g0 * sgate[r]);
;         OT[li + 16] = f2bf(o[1][r] * rstd * g1 * sgate[4 + r]);
;       }
;     }
;     __syncthreads();
;     *(u32x4*)(p.O + ((size_t)b * SEQ + n * 16 + (tid >> 4)) * DM + ocol + (tid & 15) * 8) = *(const u32x4*)&OT[(tid >> 4) * 136 + (tid & 15) * 8];
.Lrec_gla_dr0:
	s_add_u32 s12, s12, 0x8000
	s_addc_u32 s13, s13, 0
	s_waitcnt lgkmcnt(0)
	s_waitcnt lgkmcnt(0)
	v_pk_add_f32 v[220:221], v[204:205], v[208:209]
	v_pk_add_f32 v[222:223], v[206:207], v[210:211]
	v_pk_add_f32 v[220:221], v[220:221], v[212:213]
	v_pk_add_f32 v[222:223], v[222:223], v[214:215]
	v_pk_add_f32 v[220:221], v[220:221], v[216:217]
	v_pk_add_f32 v[222:223], v[222:223], v[218:219]
	v_fma_f32 v220, v220, s30, v177
	v_fma_f32 v221, v221, s30, v177
	v_fma_f32 v222, v222, s30, v177
	v_fma_f32 v223, v223, s30, v177
	v_rsq_f32_e32 v220, v220
	v_rsq_f32_e32 v221, v221
	v_rsq_f32_e32 v222, v222
	v_rsq_f32_e32 v223, v223
	s_nop 0
	v_mul_f32_e32 v204, v194, v220
	v_mul_f32_e32 v205, v195, v221
	v_mul_f32_e32 v206, v196, v222
	v_mul_f32_e32 v207, v197, v223
	v_mul_f32_e32 v208, v198, v220
	v_mul_f32_e32 v209, v199, v221
	v_mul_f32_e32 v210, v200, v222
	v_mul_f32_e32 v211, v201, v223
	v_mul_f32_e32 v204, v175, v204
	v_mul_f32_e32 v205, v175, v205
	v_mul_f32_e32 v206, v175, v206
	v_mul_f32_e32 v207, v175, v207
	v_mul_f32_e32 v208, v176, v208
	v_mul_f32_e32 v209, v176, v209
	v_mul_f32_e32 v210, v176, v210
	v_mul_f32_e32 v211, v176, v211
	ds_write_b32 v149, v204 offset:47872
	ds_write_b32 v149, v205 offset:48400
	ds_write_b32 v149, v206 offset:48928
	ds_write_b32 v149, v207 offset:49456
	ds_write_b32 v149, v208 offset:47936
	ds_write_b32 v149, v209 offset:48464
	ds_write_b32 v149, v210 offset:48992
	ds_write_b32 v149, v211 offset:49520
	s_waitcnt lgkmcnt(0)
	s_barrier
	ds_read_b128 v[224:227], v150 offset:47872
	ds_read_b128 v[228:231], v150 offset:47888
	s_waitcnt lgkmcnt(0)
	v_lshlrev_b32_e32 v232, 16, v44
	v_and_b32_e32 v233, 0xffff0000, v44
	v_lshlrev_b32_e32 v234, 16, v45
	v_and_b32_e32 v235, 0xffff0000, v45
	v_lshlrev_b32_e32 v236, 16, v46
	v_and_b32_e32 v237, 0xffff0000, v46
	v_lshlrev_b32_e32 v238, 16, v47
	v_and_b32_e32 v239, 0xffff0000, v47
	v_pk_mul_f32 v[224:225], v[224:225], v[232:233]
	v_pk_mul_f32 v[226:227], v[226:227], v[234:235]
	v_pk_mul_f32 v[228:229], v[228:229], v[236:237]
	v_pk_mul_f32 v[230:231], v[230:231], v[238:239]
	v_cvt_pk_bf16_f32 v232, v224, v225
	v_cvt_pk_bf16_f32 v233, v226, v227
	v_cvt_pk_bf16_f32 v234, v228, v229
	v_cvt_pk_bf16_f32 v235, v230, v231
	s_cmp_lt_u32 s36, 2
	s_cbranch_scc1 .Lrec_gla_dr1
	global_store_dwordx4 v174, v[232:235], s[12:13]

; template <int DK, bool HG, int MODE>
; __device__ void recur_unit(const Params& p, char* smem, int b, int h, char* img, int nstart, int nstep, int nend) {
;     ...
;   const int tid = threadIdx.x, lane = tid & 63, w = tid >> 6, l15 = lane & 15, kg = lane >> 4;
;   const int t = tid & 15, kgp = tid >> 4, k0 = kgp * KPT;
;   const int qcol = HG ? (h * 128) : (2048 + h * 64);
;   const int kcol = HG ? (512 + h * 128) : (2304 + h * 64);
;   const int vcol = HG ? (1024 + h * 128) : (2560 + h * 128);
;   const int gcol = HG ? (1536 + h * 128) : (3088 + h * 128);
;   const int ocol = HG ? (h * 128) : (512 + h * 128);
;   const float* gain = HG ? p.norm_h : p.norm_g;
;   float ba[KPT];
;   if (!HG && MODE == 1) {
;     __syncthreads();
;     for (int i = tid; i < 16 * 64; i += 256) Wa[i] = p.w_a2[(i >> 6) * 256 + h * 64 + (i & 63)];
; #pragma unroll
;     for (int i = 0; i < KPT; i++) ba[i] = p.b_a[h * 64 + k0 + i];
;     __syncthreads();
;   }
;   const float g0 = gain[h * 128 + w * 32 + l15], g1 = gain[h * 128 + w * 32 + 16 + l15];
;   f32x4 S[NKT][2];
; #pragma unroll
;   for (int i = 0; i < NKT; i++) { S[i][0] = f32x4{0, 0, 0, 0}; S[i][1] = f32x4{0, 0, 0, 0}; }
;   float4 pl[4];
;   uint4 pq, pk, pv;
;   u16 psg[8];
;   u32x4 imA[NIM], imB[NIM];
;   u16 psgB[8];
;   auto prefetch = [&](int n, u32x4 (&im)[NIM], u16 (&psg)[8]) {
;     if (MODE == 2) {
;       const char* src = img + (size_t)n * IMG;
; #pragma unroll
;       for (int i = 0; i < NIM; i++) if (tid * 16 + 4096 * i < IMG) im[i] = *(const u32x4*)(src + tid * 16 + 4096 * i);
;       {
;         const u32x4 g = *(const u32x4*)(p.P + ((size_t)b * SEQ + n * 16 + (tid >> 4)) * INC + gcol + (tid & 15) * 8);
;     ...
;   if (MODE == 2) {
;     prefetch(0, imA, psg);
;     prefetch(1, imB, psgB);
;     for (int n = 0; n < SEQ / 16; n += 2) {
;       if (n == 62) mid_barrier(p, smem);
;       step(n, imA, psg); step(n + 1, imB, psgB);
;     }
.Lrec_hg_entry:
	v_readlane_b32 s6, v240, 52
	v_readlane_b32 s2, v240, 24
	v_readlane_b32 s3, v240, 25
	s_nop 3
	s_mul_i32 s26, s6, 0x260000
	s_mul_hi_u32 s27, s6, 0x260000
	s_add_u32 s8, s78, s26
	s_addc_u32 s9, s79, s27
	s_lshr_b32 s26, s6, 2
	s_and_b32 s27, s6, 3
	s_mul_i32 s28, s26, 0xe10000
	s_add_u32 s10, s88, s28
	s_addc_u32 s11, s89, 0
	s_lshl_b32 s28, s27, 8
	s_add_u32 s28, s28, 0xc00
	s_add_u32 s10, s10, s28
	s_addc_u32 s11, s11, 0
	s_lshl_b32 s28, s26, 22
	s_add_u32 s12, s2, s28
	s_addc_u32 s13, s3, 0
	s_lshl_b32 s28, s27, 8
	s_add_u32 s12, s12, s28
	s_addc_u32 s13, s13, 0
	s_sub_u32 s12, s12, 0x10000
	s_subb_u32 s13, s13, 0
	s_mov_b32 s30, 0x3c000000
	s_mov_b32 s4, 0
	s_mov_b32 s36, 0
	v_and_b32_e32 v137, 15, v128
	v_bfe_u32 v139, v128, 4, 2
	v_lshrrev_b32_e32 v142, 6, v128
	v_lshrrev_b32_e32 v178, 4, v128
	v_mul_u32_u24_e32 v202, 272, v137
	v_lshl_add_u32 v144, v139, 3, v202
	v_lshl_add_u32 v202, v142, 5, v137
	v_mul_u32_u24_e32 v202, 40, v202
	v_lshl_add_u32 v145, v139, 3, v202
	v_mul_u32_u24_e32 v202, 40, v137
	v_lshl_add_u32 v146, v139, 3, v202
	v_lshlrev_b32_e32 v147, 4, v139
	v_lshl_add_u32 v148, v142, 6, v147
	v_mul_u32_u24_e32 v202, 0x840, v139
	v_lshl_add_u32 v202, v142, 7, v202
	v_lshl_add_u32 v149, v137, 2, v202
	v_mul_u32_u24_e32 v202, 0x210, v178
	v_lshl_add_u32 v150, v137, 5, v202
	v_lshlrev_b32_e32 v151, 4, v128
	v_add_u32_e32 v152, 0x0, v151
	v_add_u32_e32 v153, 0x1000, v151
	v_add_u32_e32 v154, 0x2000, v151
	v_add_u32_e32 v155, 0x3000, v151
	v_add_u32_e32 v172, 0x4000, v151
	s_movk_i32 s28, 192
	v_cmp_gt_u32_e64 s[24:25], s28, v128
	s_nop 1
	v_cndmask_b32_e64 v172, 0, v172, s[24:25]
	v_mul_u32_u24_e32 v202, 0x1c20, v178
	v_lshl_add_u32 v173, v137, 4, v202
	v_lshlrev_b32_e32 v202, 11, v178
	v_lshl_add_u32 v174, v137, 4, v202
	v_lshl_add_u32 v202, v142, 5, v137
	s_lshl_b32 s28, s27, 7
	v_add_lshl_u32 v202, s28, v202, 2
	global_load_dword v175, v202, s[62:63]
	global_load_dword v176, v202, s[62:63] offset:64
	v_lshlrev_b32_e32 v203, 2, v139
	v_cmp_gt_u32_e64 s[14:15], v203, v137
	v_add_u32_e32 v184, 1, v203
	v_cmp_gt_u32_e64 s[16:17], v184, v137
	v_add_u32_e32 v184, 2, v203
	v_cmp_gt_u32_e64 s[18:19], v184, v137
	v_add_u32_e32 v184, 3, v203
	v_cmp_gt_u32_e64 s[20:21], v184, v137
	v_cmp_eq_u32_e64 s[22:23], 0, v137
	v_mov_b32_e32 v177, 0x3727c5ac
	v_mov_b32_e32 v48, 0
	v_mov_b32_e32 v49, 0
	v_mov_b32_e32 v50, 0
	v_mov_b32_e32 v51, 0
	v_mov_b32_e32 v52, 0
	v_mov_b32_e32 v53, 0
	v_mov_b32_e32 v54, 0
	v_mov_b32_e32 v55, 0
	v_mov_b32_e32 v56, 0
	v_mov_b32_e32 v57, 0
	v_mov_b32_e32 v58, 0
	v_mov_b32_e32 v59, 0
	v_mov_b32_e32 v60, 0
	v_mov_b32_e32 v61, 0
	v_mov_b32_e32 v62, 0
	v_mov_b32_e32 v63, 0
	v_mov_b32_e32 v64, 0
	v_mov_b32_e32 v65, 0
	v_mov_b32_e32 v66, 0
	v_mov_b32_e32 v67, 0
	v_mov_b32_e32 v68, 0
	v_mov_b32_e32 v69, 0
	v_mov_b32_e32 v70, 0
	v_mov_b32_e32 v71, 0
	v_mov_b32_e32 v72, 0
	v_mov_b32_e32 v73, 0
	v_mov_b32_e32 v74, 0
	v_mov_b32_e32 v75, 0
	v_mov_b32_e32 v76, 0
	v_mov_b32_e32 v77, 0
	v_mov_b32_e32 v78, 0
	v_mov_b32_e32 v79, 0
	v_mov_b32_e32 v80, 0
	v_mov_b32_e32 v81, 0
	v_mov_b32_e32 v82, 0
	v_mov_b32_e32 v83, 0
	v_mov_b32_e32 v84, 0
	v_mov_b32_e32 v85, 0
	v_mov_b32_e32 v86, 0
	v_mov_b32_e32 v87, 0
	v_mov_b32_e32 v88, 0
	v_mov_b32_e32 v89, 0
	v_mov_b32_e32 v90, 0
	v_mov_b32_e32 v91, 0
	v_mov_b32_e32 v92, 0
	v_mov_b32_e32 v93, 0
	v_mov_b32_e32 v94, 0
	v_mov_b32_e32 v95, 0
	v_mov_b32_e32 v96, 0
	v_mov_b32_e32 v97, 0
	v_mov_b32_e32 v98, 0
	v_mov_b32_e32 v99, 0
	v_mov_b32_e32 v100, 0
	v_mov_b32_e32 v101, 0
	v_mov_b32_e32 v102, 0
	v_mov_b32_e32 v103, 0
	v_mov_b32_e32 v104, 0
	v_mov_b32_e32 v105, 0
	v_mov_b32_e32 v106, 0
	v_mov_b32_e32 v107, 0
	v_mov_b32_e32 v108, 0
	v_mov_b32_e32 v109, 0
	v_mov_b32_e32 v110, 0
	v_mov_b32_e32 v111, 0
	global_load_dwordx4 v[0:3], v152, s[8:9]
	global_load_dwordx4 v[4:7], v153, s[8:9]
	global_load_dwordx4 v[8:11], v154, s[8:9]
	global_load_dwordx4 v[12:15], v155, s[8:9]
	global_load_dwordx4 v[16:19], v172, s[8:9]
	s_add_u32 s8, s8, 0x4c00
	s_addc_u32 s9, s9, 0
	global_load_dwordx4 v[20:23], v152, s[8:9]
	global_load_dwordx4 v[24:27], v153, s[8:9]
	global_load_dwordx4 v[28:31], v154, s[8:9]
	global_load_dwordx4 v[32:35], v155, s[8:9]
	global_load_dwordx4 v[36:39], v172, s[8:9]
	s_add_u32 s8, s8, 0x4c00
	s_addc_u32 s9, s9, 0
	s_waitcnt vmcnt(5)
	ds_write_b128 v151, v[0:3] offset:0
	ds_write_b128 v151, v[4:7] offset:4096
	ds_write_b128 v151, v[8:11] offset:8192
	ds_write_b128 v151, v[12:15] offset:12288
	s_mov_b64 s[26:27], exec
	s_and_b64 exec, exec, s[24:25]
	ds_write_b128 v151, v[16:19] offset:16384
	s_mov_b64 exec, s[26:27]
	global_load_dwordx4 v[0:3], v152, s[8:9]
	global_load_dwordx4 v[4:7], v153, s[8:9]
	global_load_dwordx4 v[8:11], v154, s[8:9]
	global_load_dwordx4 v[12:15], v155, s[8:9]
	global_load_dwordx4 v[16:19], v172, s[8:9]
	s_add_u32 s8, s8, 0x4c00
	s_addc_u32 s9, s9, 0
	s_waitcnt lgkmcnt(0)
	.p2align 3
	s_nop 0

; #define STAGE() do { } while (0)
; template <int DK, bool HG, int MODE>
; __device__ void recur_unit(const Params& p, char* smem, int b, int h, char* img, int nstart, int nstep, int nend) {
;     ...
;     f32x4 sc = f32x4{0, 0, 0, 0};
;     bf16x8 qf[NKS];
; #pragma unroll
;     for (int st = 0; st < NKS; st++) {
;       bf16x4 q0 = *(const bf16x4*)&Qt[l15 * LQ + 32 * st + kg * 4];
;       bf16x4 q1 = *(const bf16x4*)&Qt[l15 * LQ + 32 * st + 16 + kg * 4];
;       bf16x4 c0 = *(const bf16x4*)&Kt[l15 * LQ + 32 * st + kg * 4];
;       bf16x4 c1 = *(const bf16x4*)&Kt[l15 * LQ + 32 * st + 16 + kg * 4];
;       qf[st] = bf16x8{q0[0], q0[1], q0[2], q0[3], q1[0], q1[1], q1[2], q1[3]};
;       bf16x8 kf = bf16x8{c0[0], c0[1], c0[2], c0[3], c1[0], c1[1], c1[2], c1[3]};
;       sc = __builtin_amdgcn_mfma_f32_16x16x32_bf16(kf, qf[st], sc, 0, 0, 0);
;     }
;     STAGE();
; #pragma unroll
;     for (int r = 0; r < 4; r++) if (kg * 4 + r > l15) sc[r] = 0.f;
;     bf16x4 pA;
;     {
;       unsigned a = pack2(sc[0], sc[1]), c = pack2(sc[2], sc[3]);
;       pA = bf16x4{(short)(a & 0xffff), (short)(a >> 16), (short)(c & 0xffff), (short)(c >> 16)};
;     }
;     bf16x4 vf[2];
;     f32x4 o[2], oin[2];
;     bf16x8 sbv[2][NKS];
; #pragma unroll
;     for (int vt = 0; vt < 2; vt++) {
;       vf[vt] = *(const bf16x4*)&VT[(w * 32 + vt * 16 + l15) * 20 + kg * 4];
; #pragma unroll
;       for (int st = 0; st < NKS; st++) {
;         unsigned s0 = pack2(S[2 * st][vt][0], S[2 * st][vt][1]), s1 = pack2(S[2 * st][vt][2], S[2 * st][vt][3]);
;         unsigned s2 = pack2(S[2 * st + 1][vt][0], S[2 * st + 1][vt][1]), s3 = pack2(S[2 * st + 1][vt][2], S[2 * st + 1][vt][3]);
;         sbv[vt][st] = bf16x8{(short)(s0 & 0xffff), (short)(s0 >> 16), (short)(s1 & 0xffff), (short)(s1 >> 16),
;                            (short)(s2 & 0xffff), (short)(s2 >> 16), (short)(s3 & 0xffff), (short)(s3 >> 16)};
;       }
;     }
;     STAGE();
; #pragma unroll
;     for (int vt = 0; vt < 2; vt++) {
;       o[vt] = __builtin_amdgcn_mfma_f32_16x16x16bf16_1k(pA, vf[vt], f32x4{0, 0, 0, 0}, 0, 0, 0);
;       oin[vt] = f32x4{0, 0, 0, 0};
; #pragma unroll
;       for (int st = 0; st < NKS; st++) oin[vt] = __builtin_amdgcn_mfma_f32_16x16x32_bf16(qf[st], sbv[vt][st], oin[vt], 0, 0, 0);
;     }
;     STAGE();
;     bf16x4 khf[NKT];
; #pragma unroll
;     for (int kt2 = 0; kt2 < NKT; kt2++) {
.Lrec_hg_p0_nost:
	global_load_dwordx4 v[40:43], v173, s[10:11]
	s_add_u32 s10, s10, 0x1c200
	s_addc_u32 s11, s11, 0
	s_add_u32 s12, s12, 0x8000
	s_addc_u32 s13, s13, 0
	ds_read_b64 v[224:225], v144 offset:4416
	ds_read_b64 v[226:227], v144 offset:4448
	ds_read_b64 v[228:229], v144 offset:64
	ds_read_b64 v[230:231], v144 offset:96
	ds_read_b64 v[232:233], v146 offset:9984
	ds_read_b64 v[234:235], v146 offset:10624
	ds_read_b128 v[236:239], v147 offset:19072
	ds_read_b128 v[112:115], v147 offset:19136
	s_waitcnt lgkmcnt(14)
	v_mfma_f32_16x16x32_bf16 a[0:3], v[204:207], v[208:211], 0
	v_mfma_f32_16x16x32_bf16 a[4:7], v[208:211], v[120:123], 0
	v_mfma_f32_16x16x32_bf16 a[8:11], v[208:211], v[156:159], 0
	s_waitcnt lgkmcnt(8)
	v_pk_mul_f32 v[48:49], v[48:49], v[216:217]
	v_pk_mul_f32 v[50:51], v[50:51], v[218:219]
	v_pk_mul_f32 v[52:53], v[52:53], v[216:217]
	v_pk_mul_f32 v[54:55], v[54:55], v[218:219]
	v_mfma_f32_16x16x16_bf16 v[48:51], v[212:213], v[116:117], v[48:51]
	v_pk_mul_f32 v[56:57], v[56:57], v[220:221]
	v_pk_mul_f32 v[58:59], v[58:59], v[222:223]
	v_mfma_f32_16x16x16_bf16 v[52:55], v[212:213], v[118:119], v[52:55]
	v_pk_mul_f32 v[60:61], v[60:61], v[220:221]
	v_pk_mul_f32 v[62:63], v[62:63], v[222:223]
	v_mfma_f32_16x16x16_bf16 v[56:59], v[214:215], v[116:117], v[56:59]
	v_cvt_pk_bf16_f32 v120, v64, v65
	v_cvt_pk_bf16_f32 v121, v66, v67
	v_mfma_f32_16x16x16_bf16 v[60:63], v[214:215], v[118:119], v[60:63]
	v_cvt_pk_bf16_f32 v122, v72, v73
	v_cvt_pk_bf16_f32 v123, v74, v75
	v_cvt_pk_bf16_f32 v156, v68, v69
	v_cvt_pk_bf16_f32 v157, v70, v71
	v_cvt_pk_bf16_f32 v158, v76, v77
	v_cvt_pk_bf16_f32 v159, v78, v79
	ds_read_b64 v[204:205], v144 offset:4480
	ds_read_b64 v[206:207], v144 offset:4512
	ds_read_b64 v[208:209], v144 offset:128
	ds_read_b64 v[210:211], v144 offset:160
	ds_read_b64 v[212:213], v146 offset:11264
	ds_read_b64 v[214:215], v146 offset:11904
	ds_read_b128 v[216:219], v147 offset:19200
	ds_read_b128 v[220:223], v147 offset:19264
	s_waitcnt lgkmcnt(12)
	v_mfma_f32_16x16x32_bf16 a[0:3], v[224:227], v[228:231], a[0:3]
	v_mfma_f32_16x16x32_bf16 a[4:7], v[228:231], v[120:123], a[4:7]
	v_mfma_f32_16x16x32_bf16 a[8:11], v[228:231], v[156:159], a[8:11]
	s_waitcnt lgkmcnt(8)
	v_pk_mul_f32 v[64:65], v[64:65], v[236:237]
	v_pk_mul_f32 v[66:67], v[66:67], v[238:239]
	v_pk_mul_f32 v[68:69], v[68:69], v[236:237]
	v_pk_mul_f32 v[70:71], v[70:71], v[238:239]
	v_mfma_f32_16x16x16_bf16 v[64:67], v[232:233], v[116:117], v[64:67]
	v_pk_mul_f32 v[72:73], v[72:73], v[112:113]
	v_pk_mul_f32 v[74:75], v[74:75], v[114:115]
	v_mfma_f32_16x16x16_bf16 v[68:71], v[232:233], v[118:119], v[68:71]
	v_pk_mul_f32 v[76:77], v[76:77], v[112:113]
	v_pk_mul_f32 v[78:79], v[78:79], v[114:115]
	v_mfma_f32_16x16x16_bf16 v[72:75], v[234:235], v[116:117], v[72:75]
	v_cvt_pk_bf16_f32 v120, v80, v81
	v_cvt_pk_bf16_f32 v121, v82, v83
	v_mfma_f32_16x16x16_bf16 v[76:79], v[234:235], v[118:119], v[76:79]
	v_cvt_pk_bf16_f32 v122, v88, v89
	v_cvt_pk_bf16_f32 v123, v90, v91
	v_cvt_pk_bf16_f32 v156, v84, v85
	v_cvt_pk_bf16_f32 v157, v86, v87
	v_cvt_pk_bf16_f32 v158, v92, v93
	v_cvt_pk_bf16_f32 v159, v94, v95
	ds_read_b64 v[224:225], v144 offset:4544
	ds_read_b64 v[226:227], v144 offset:4576
	ds_read_b64 v[228:229], v144 offset:192
	ds_read_b64 v[230:231], v144 offset:224
	ds_read_b64 v[232:233], v146 offset:12544
	ds_read_b64 v[234:235], v146 offset:13184
	ds_read_b128 v[236:239], v147 offset:19328
	ds_read_b128 v[112:115], v147 offset:19392
	s_waitcnt lgkmcnt(12)
	v_mfma_f32_16x16x32_bf16 a[0:3], v[204:207], v[208:211], a[0:3]
	v_mfma_f32_16x16x32_bf16 a[4:7], v[208:211], v[120:123], a[4:7]
	v_mfma_f32_16x16x32_bf16 a[8:11], v[208:211], v[156:159], a[8:11]
	s_waitcnt lgkmcnt(8)
	v_pk_mul_f32 v[80:81], v[80:81], v[216:217]
	v_pk_mul_f32 v[82:83], v[82:83], v[218:219]
	v_pk_mul_f32 v[84:85], v[84:85], v[216:217]
	v_pk_mul_f32 v[86:87], v[86:87], v[218:219]
	v_mfma_f32_16x16x16_bf16 v[80:83], v[212:213], v[116:117], v[80:83]
	v_pk_mul_f32 v[88:89], v[88:89], v[220:221]
	v_pk_mul_f32 v[90:91], v[90:91], v[222:223]
	v_mfma_f32_16x16x16_bf16 v[84:87], v[212:213], v[118:119], v[84:87]
	v_pk_mul_f32 v[92:93], v[92:93], v[220:221]
	v_pk_mul_f32 v[94:95], v[94:95], v[222:223]
	v_mfma_f32_16x16x16_bf16 v[88:91], v[214:215], v[116:117], v[88:91]
	v_cvt_pk_bf16_f32 v120, v96, v97
	v_cvt_pk_bf16_f32 v121, v98, v99
	v_mfma_f32_16x16x16_bf16 v[92:95], v[214:215], v[118:119], v[92:95]
	v_cvt_pk_bf16_f32 v122, v104, v105
	v_cvt_pk_bf16_f32 v123, v106, v107
	v_cvt_pk_bf16_f32 v156, v100, v101
	v_cvt_pk_bf16_f32 v157, v102, v103
	v_cvt_pk_bf16_f32 v158, v108, v109
	v_cvt_pk_bf16_f32 v159, v110, v111
	s_waitcnt lgkmcnt(4)
	v_mfma_f32_16x16x32_bf16 a[0:3], v[224:227], v[228:231], a[0:3]
	v_mfma_f32_16x16x32_bf16 a[4:7], v[228:231], v[120:123], a[4:7]
	v_mfma_f32_16x16x32_bf16 a[8:11], v[228:231], v[156:159], a[8:11]
	s_waitcnt lgkmcnt(0)
; __device__ __forceinline__ float bf2f(u16 v) { return __uint_as_float(((unsigned)v) << 16); }
; #define STAGE() do { } while (0)
; template <int DK, bool HG, int MODE>
; __device__ void recur_unit(const Params& p, char* smem, int b, int h, char* img, int nstart, int nstep, int nend) {
;     ...
; #pragma unroll
;     for (int vt = 0; vt < 2; vt++) {
;       o[vt] = __builtin_amdgcn_mfma_f32_16x16x16bf16_1k(pA, vf[vt], f32x4{0, 0, 0, 0}, 0, 0, 0);
;       oin[vt] = f32x4{0, 0, 0, 0};
; #pragma unroll
;       for (int st = 0; st < NKS; st++) oin[vt] = __builtin_amdgcn_mfma_f32_16x16x32_bf16(qf[st], sbv[vt][st], oin[vt], 0, 0, 0);
;     }
;     STAGE();
;     bf16x4 khf[NKT];
; #pragma unroll
;     for (int kt2 = 0; kt2 < NKT; kt2++) {
;       khf[kt2] = *(const bf16x4*)&KhT[(16 * kt2 + l15) * 20 + kg * 4];
;       float4 g4 = *(const float4*)&Gch[16 * kt2 + kg * 4];
;       f32x4 gv = f32x4{g4.x, g4.y, g4.z, g4.w};
;       S[kt2][0] *= gv; S[kt2][1] *= gv;
;     }
;     STAGE();
; #pragma unroll
;     for (int kt2 = 0; kt2 < NKT; kt2++) {
; #pragma unroll
;       for (int vt = 0; vt < 2; vt++)
;         S[kt2][vt] = __builtin_amdgcn_mfma_f32_16x16x16bf16_1k(khf[kt2], vf[vt], S[kt2][vt], 0, 0, 0);
;     }
;     STAGE();
;     float ss[4];
; #pragma unroll
;     for (int r = 0; r < 4; r++) {
;       o[0][r] += oin[0][r]; o[1][r] += oin[1][r];
;       float s = o[0][r] * o[0][r] + o[1][r] * o[1][r];
;       s = dpp_row_sum(s);
;       ss[r] = s;
;     }
;     if (l15 == 0) *(float4*)&SS[w * 16 + kg * 4] = make_float4(ss[0], ss[1], ss[2], ss[3]);
;     __syncthreads();
;     {
;       float4 a0 = *(const float4*)&SS[0 * 16 + kg * 4], a1 = *(const float4*)&SS[1 * 16 + kg * 4];
;       float4 a2 = *(const float4*)&SS[2 * 16 + kg * 4], a3 = *(const float4*)&SS[3 * 16 + kg * 4];
;       float tot[4] = {a0.x + a1.x + a2.x + a3.x, a0.y + a1.y + a2.y + a3.y, a0.z + a1.z + a2.z + a3.z, a0.w + a1.w + a2.w + a3.w};
; #pragma unroll
;       for (int r = 0; r < 4; r++) {
;         const float rstd = rsqrtf(tot[r] * (1.f / 128.f) + LN_EPS);
;         const int li = (kg * 4 + r) * 136 + w * 32 + l15;
;         sgate[r] = bf2f(GT[li]); sgate[4 + r] = bf2f(GT[li + 16]);
;         OT[li] = f2bf(o[0][r] * rstd * g0 * sgate[r]);
;         OT[li + 16] = f2bf(o[1][r] * rstd * g1 * sgate[4 + r]);
;       }
	v_pk_mul_f32 v[96:97], v[96:97], v[236:237]
	v_pk_mul_f32 v[98:99], v[98:99], v[238:239]
	v_pk_mul_f32 v[100:101], v[100:101], v[236:237]
	v_pk_mul_f32 v[102:103], v[102:103], v[238:239]
	v_mfma_f32_16x16x16_bf16 v[96:99], v[232:233], v[116:117], v[96:99]
	v_pk_mul_f32 v[104:105], v[104:105], v[112:113]
	v_pk_mul_f32 v[106:107], v[106:107], v[114:115]
	v_mfma_f32_16x16x16_bf16 v[100:103], v[232:233], v[118:119], v[100:103]
	v_pk_mul_f32 v[108:109], v[108:109], v[112:113]
	v_pk_mul_f32 v[110:111], v[110:111], v[114:115]
	v_mfma_f32_16x16x16_bf16 v[104:107], v[234:235], v[116:117], v[104:107]
	s_nop 1
	v_mfma_f32_16x16x16_bf16 v[108:111], v[234:235], v[118:119], v[108:111]
	ds_read_b128 v[204:207], v147 offset:39168
	ds_read_b128 v[208:211], v147 offset:39232
	ds_read_b128 v[212:215], v147 offset:39296
	ds_read_b128 v[216:219], v147 offset:39360
	v_accvgpr_read_b32 v224, a0
	v_accvgpr_read_b32 v225, a1
	v_accvgpr_read_b32 v226, a2
	v_accvgpr_read_b32 v227, a3
	v_cndmask_b32_e64 v224, v224, 0, s[14:15]
	v_cndmask_b32_e64 v225, v225, 0, s[16:17]
	v_cndmask_b32_e64 v226, v226, 0, s[18:19]
	v_cndmask_b32_e64 v227, v227, 0, s[20:21]
	v_cvt_pk_bf16_f32 v140, v224, v225
	v_cvt_pk_bf16_f32 v141, v226, v227
	s_nop 1
	v_mfma_f32_16x16x16_bf16 v[186:189], v[140:141], v[116:117], 0
	v_mfma_f32_16x16x16_bf16 v[190:193], v[140:141], v[118:119], 0
	v_accvgpr_read_b32 v228, a4
	v_accvgpr_read_b32 v229, a5
	v_accvgpr_read_b32 v230, a6
	v_accvgpr_read_b32 v231, a7
	v_accvgpr_read_b32 v232, a8
	v_accvgpr_read_b32 v233, a9
	v_accvgpr_read_b32 v234, a10
	v_accvgpr_read_b32 v235, a11
	s_nop 1
	v_pk_add_f32 v[186:187], v[186:187], v[228:229]
	v_pk_add_f32 v[188:189], v[188:189], v[230:231]
	v_pk_add_f32 v[190:191], v[190:191], v[232:233]
	v_pk_add_f32 v[192:193], v[192:193], v[234:235]
	v_pk_mul_f32 v[236:237], v[190:191], v[190:191]
	v_pk_mul_f32 v[238:239], v[192:193], v[192:193]
	v_pk_fma_f32 v[112:113], v[186:187], v[186:187], v[236:237]
	v_pk_fma_f32 v[114:115], v[188:189], v[188:189], v[238:239]
	s_nop 1
	v_add_f32_dpp v112, v112, v112 row_ror:8 row_mask:0xf bank_mask:0xf
	v_add_f32_dpp v113, v113, v113 row_ror:8 row_mask:0xf bank_mask:0xf
	v_add_f32_dpp v114, v114, v114 row_ror:8 row_mask:0xf bank_mask:0xf
	v_add_f32_dpp v115, v115, v115 row_ror:8 row_mask:0xf bank_mask:0xf
	v_add_f32_dpp v112, v112, v112 row_ror:4 row_mask:0xf bank_mask:0xf
	v_add_f32_dpp v113, v113, v113 row_ror:4 row_mask:0xf bank_mask:0xf
	v_add_f32_dpp v114, v114, v114 row_ror:4 row_mask:0xf bank_mask:0xf
	v_add_f32_dpp v115, v115, v115 row_ror:4 row_mask:0xf bank_mask:0xf
	v_add_f32_dpp v112, v112, v112 row_ror:2 row_mask:0xf bank_mask:0xf
	v_add_f32_dpp v113, v113, v113 row_ror:2 row_mask:0xf bank_mask:0xf
	v_add_f32_dpp v114, v114, v114 row_ror:2 row_mask:0xf bank_mask:0xf
	v_add_f32_dpp v115, v115, v115 row_ror:2 row_mask:0xf bank_mask:0xf
	v_add_f32_dpp v112, v112, v112 row_ror:1 row_mask:0xf bank_mask:0xf
	v_add_f32_dpp v113, v113, v113 row_ror:1 row_mask:0xf bank_mask:0xf
	v_add_f32_dpp v114, v114, v114 row_ror:1 row_mask:0xf bank_mask:0xf
	v_add_f32_dpp v115, v115, v115 row_ror:1 row_mask:0xf bank_mask:0xf
	s_mov_b64 s[26:27], exec
	s_and_b64 exec, exec, s[22:23]
	ds_write_b128 v148, v[112:115] offset:38912
	s_mov_b64 exec, s[26:27]
	s_waitcnt lgkmcnt(1)
	v_pk_add_f32 v[220:221], v[204:205], v[208:209]
	v_pk_add_f32 v[222:223], v[206:207], v[210:211]
	v_pk_add_f32 v[220:221], v[220:221], v[212:213]
	v_pk_add_f32 v[222:223], v[222:223], v[214:215]
	v_pk_add_f32 v[220:221], v[220:221], v[216:217]
	v_pk_add_f32 v[222:223], v[222:223], v[218:219]
	v_fma_f32 v220, v220, s30, v177
	v_fma_f32 v221, v221, s30, v177
	v_fma_f32 v222, v222, s30, v177
	v_fma_f32 v223, v223, s30, v177
	v_rsq_f32_e32 v220, v220
	v_rsq_f32_e32 v221, v221
	v_rsq_f32_e32 v222, v222
	v_rsq_f32_e32 v223, v223
	s_nop 0
	v_mul_f32_e32 v204, v194, v220
	v_mul_f32_e32 v205, v195, v221
	v_mul_f32_e32 v206, v196, v222
	v_mul_f32_e32 v207, v197, v223
	v_mul_f32_e32 v208, v198, v220
	v_mul_f32_e32 v209, v199, v221
	v_mul_f32_e32 v210, v200, v222
	v_mul_f32_e32 v211, v201, v223
	v_mul_f32_e32 v204, v175, v204
	v_mul_f32_e32 v205, v175, v205
	v_mul_f32_e32 v206, v175, v206
	v_mul_f32_e32 v207, v175, v207
	v_mul_f32_e32 v208, v176, v208
	v_mul_f32_e32 v209, v176, v209
	v_mul_f32_e32 v210, v176, v210
	v_mul_f32_e32 v211, v176, v211
	ds_write_b32 v149, v204 offset:47872
	ds_write_b32 v149, v205 offset:48400
	ds_write_b32 v149, v206 offset:48928
	ds_write_b32 v149, v207 offset:49456
	ds_write_b32 v149, v208 offset:47936
	ds_write_b32 v149, v209 offset:48464
	ds_write_b32 v149, v210 offset:48992
	ds_write_b32 v149, v211 offset:49520
	s_cmp_lg_u32 s29, 0
	s_cbranch_scc1 .Lrec_hg_p0w_d
	s_waitcnt vmcnt(9)
	s_branch .Lrec_hg_p0w_c

; template <int DK, bool HG, int MODE>
; __device__ void recur_unit(const Params& p, char* smem, int b, int h, char* img, int nstart, int nstep, int nend) {
;     ...
;     for (int st = 0; st < NKS; st++) {
;       bf16x4 q0 = *(const bf16x4*)&Qt[l15 * LQ + 32 * st + kg * 4];
;       bf16x4 q1 = *(const bf16x4*)&Qt[l15 * LQ + 32 * st + 16 + kg * 4];
;       bf16x4 c0 = *(const bf16x4*)&Kt[l15 * LQ + 32 * st + kg * 4];
;       bf16x4 c1 = *(const bf16x4*)&Kt[l15 * LQ + 32 * st + 16 + kg * 4];
;       qf[st] = bf16x8{q0[0], q0[1], q0[2], q0[3], q1[0], q1[1], q1[2], q1[3]};
;       bf16x8 kf = bf16x8{c0[0], c0[1], c0[2], c0[3], c1[0], c1[1], c1[2], c1[3]};
;       sc = __builtin_amdgcn_mfma_f32_16x16x32_bf16(kf, qf[st], sc, 0, 0, 0);
;     }
;     STAGE();
; #pragma unroll
;     for (int r = 0; r < 4; r++) if (kg * 4 + r > l15) sc[r] = 0.f;
;     bf16x4 pA;
;     {
;       unsigned a = pack2(sc[0], sc[1]), c = pack2(sc[2], sc[3]);
;       pA = bf16x4{(short)(a & 0xffff), (short)(a >> 16), (short)(c & 0xffff), (short)(c >> 16)};
;     }
;     bf16x4 vf[2];
;     f32x4 o[2], oin[2];
;     bf16x8 sbv[2][NKS];
; #pragma unroll
;     for (int vt = 0; vt < 2; vt++) {
;       vf[vt] = *(const bf16x4*)&VT[(w * 32 + vt * 16 + l15) * 20 + kg * 4];
; #pragma unroll
;       for (int st = 0; st < NKS; st++) {
;         unsigned s0 = pack2(S[2 * st][vt][0], S[2 * st][vt][1]), s1 = pack2(S[2 * st][vt][2], S[2 * st][vt][3]);
;         unsigned s2 = pack2(S[2 * st + 1][vt][0], S[2 * st + 1][vt][1]), s3 = pack2(S[2 * st + 1][vt][2], S[2 * st + 1][vt][3]);
;         sbv[vt][st] = bf16x8{(short)(s0 & 0xffff), (short)(s0 >> 16), (short)(s1 & 0xffff), (short)(s1 >> 16),
;                            (short)(s2 & 0xffff), (short)(s2 >> 16), (short)(s3 & 0xffff), (short)(s3 >> 16)};
;       }
;     }
;     STAGE();
; #pragma unroll
;     for (int vt = 0; vt < 2; vt++) {
;       o[vt] = __builtin_amdgcn_mfma_f32_16x16x16bf16_1k(pA, vf[vt], f32x4{0, 0, 0, 0}, 0, 0, 0);
;       oin[vt] = f32x4{0, 0, 0, 0};
; #pragma unroll
;       for (int st = 0; st < NKS; st++) oin[vt] = __builtin_amdgcn_mfma_f32_16x16x32_bf16(qf[st], sbv[vt][st], oin[vt], 0, 0, 0);
;     }
;     STAGE();
;     bf16x4 khf[NKT];
; #pragma unroll
;     for (int kt2 = 0; kt2 < NKT; kt2++) {
;       khf[kt2] = *(const bf16x4*)&KhT[(16 * kt2 + l15) * 20 + kg * 4];
;       float4 g4 = *(const float4*)&Gch[16 * kt2 + kg * 4];
.Lrec_hg_p1_nost:
	global_load_dwordx4 v[44:47], v173, s[10:11]
	s_add_u32 s10, s10, 0x1c200
	s_addc_u32 s11, s11, 0
	s_add_u32 s12, s12, 0x8000
	s_addc_u32 s13, s13, 0
	ds_read_b64 v[224:225], v144 offset:23872
	ds_read_b64 v[226:227], v144 offset:23904
	ds_read_b64 v[228:229], v144 offset:19520
	ds_read_b64 v[230:231], v144 offset:19552
	ds_read_b64 v[232:233], v146 offset:29440
	ds_read_b64 v[234:235], v146 offset:30080
	ds_read_b128 v[236:239], v147 offset:38528
	ds_read_b128 v[112:115], v147 offset:38592
	s_waitcnt lgkmcnt(14)
	v_mfma_f32_16x16x32_bf16 a[0:3], v[204:207], v[208:211], 0
	v_mfma_f32_16x16x32_bf16 a[4:7], v[208:211], v[120:123], 0
	v_mfma_f32_16x16x32_bf16 a[8:11], v[208:211], v[156:159], 0
	s_waitcnt lgkmcnt(8)
	v_pk_mul_f32 v[48:49], v[48:49], v[216:217]
	v_pk_mul_f32 v[50:51], v[50:51], v[218:219]
	v_pk_mul_f32 v[52:53], v[52:53], v[216:217]
	v_pk_mul_f32 v[54:55], v[54:55], v[218:219]
	v_mfma_f32_16x16x16_bf16 v[48:51], v[212:213], v[116:117], v[48:51]
	v_pk_mul_f32 v[56:57], v[56:57], v[220:221]
	v_pk_mul_f32 v[58:59], v[58:59], v[222:223]
	v_mfma_f32_16x16x16_bf16 v[52:55], v[212:213], v[118:119], v[52:55]
	v_pk_mul_f32 v[60:61], v[60:61], v[220:221]
	v_pk_mul_f32 v[62:63], v[62:63], v[222:223]
	v_mfma_f32_16x16x16_bf16 v[56:59], v[214:215], v[116:117], v[56:59]
	v_cvt_pk_bf16_f32 v120, v64, v65
	v_cvt_pk_bf16_f32 v121, v66, v67
	v_mfma_f32_16x16x16_bf16 v[60:63], v[214:215], v[118:119], v[60:63]
	v_cvt_pk_bf16_f32 v122, v72, v73
	v_cvt_pk_bf16_f32 v123, v74, v75
	v_cvt_pk_bf16_f32 v156, v68, v69
	v_cvt_pk_bf16_f32 v157, v70, v71
	v_cvt_pk_bf16_f32 v158, v76, v77
	v_cvt_pk_bf16_f32 v159, v78, v79
	ds_read_b64 v[204:205], v144 offset:23936
	ds_read_b64 v[206:207], v144 offset:23968
	ds_read_b64 v[208:209], v144 offset:19584
	ds_read_b64 v[210:211], v144 offset:19616
	ds_read_b64 v[212:213], v146 offset:30720
	ds_read_b64 v[214:215], v146 offset:31360
	ds_read_b128 v[216:219], v147 offset:38656
	ds_read_b128 v[220:223], v147 offset:38720
	s_waitcnt lgkmcnt(12)
	v_mfma_f32_16x16x32_bf16 a[0:3], v[224:227], v[228:231], a[0:3]
	v_mfma_f32_16x16x32_bf16 a[4:7], v[228:231], v[120:123], a[4:7]
	v_mfma_f32_16x16x32_bf16 a[8:11], v[228:231], v[156:159], a[8:11]
	s_waitcnt lgkmcnt(8)
	v_pk_mul_f32 v[64:65], v[64:65], v[236:237]
	v_pk_mul_f32 v[66:67], v[66:67], v[238:239]
	v_pk_mul_f32 v[68:69], v[68:69], v[236:237]
	v_pk_mul_f32 v[70:71], v[70:71], v[238:239]
	v_mfma_f32_16x16x16_bf16 v[64:67], v[232:233], v[116:117], v[64:67]
	v_pk_mul_f32 v[72:73], v[72:73], v[112:113]
	v_pk_mul_f32 v[74:75], v[74:75], v[114:115]
	v_mfma_f32_16x16x16_bf16 v[68:71], v[232:233], v[118:119], v[68:71]
	v_pk_mul_f32 v[76:77], v[76:77], v[112:113]
	v_pk_mul_f32 v[78:79], v[78:79], v[114:115]
	v_mfma_f32_16x16x16_bf16 v[72:75], v[234:235], v[116:117], v[72:75]
	v_cvt_pk_bf16_f32 v120, v80, v81
	v_cvt_pk_bf16_f32 v121, v82, v83
	v_mfma_f32_16x16x16_bf16 v[76:79], v[234:235], v[118:119], v[76:79]
	v_cvt_pk_bf16_f32 v122, v88, v89
	v_cvt_pk_bf16_f32 v123, v90, v91
	v_cvt_pk_bf16_f32 v156, v84, v85
	v_cvt_pk_bf16_f32 v157, v86, v87
	v_cvt_pk_bf16_f32 v158, v92, v93
	v_cvt_pk_bf16_f32 v159, v94, v95
	ds_read_b64 v[224:225], v144 offset:24000
	ds_read_b64 v[226:227], v144 offset:24032
	ds_read_b64 v[228:229], v144 offset:19648
	ds_read_b64 v[230:231], v144 offset:19680
	ds_read_b64 v[232:233], v146 offset:32000
	ds_read_b64 v[234:235], v146 offset:32640
	ds_read_b128 v[236:239], v147 offset:38784
	ds_read_b128 v[112:115], v147 offset:38848
	s_waitcnt lgkmcnt(12)
	v_mfma_f32_16x16x32_bf16 a[0:3], v[204:207], v[208:211], a[0:3]
	v_mfma_f32_16x16x32_bf16 a[4:7], v[208:211], v[120:123], a[4:7]
	v_mfma_f32_16x16x32_bf16 a[8:11], v[208:211], v[156:159], a[8:11]
	s_waitcnt lgkmcnt(8)
	v_pk_mul_f32 v[80:81], v[80:81], v[216:217]
	v_pk_mul_f32 v[82:83], v[82:83], v[218:219]
	v_pk_mul_f32 v[84:85], v[84:85], v[216:217]
	v_pk_mul_f32 v[86:87], v[86:87], v[218:219]
	v_mfma_f32_16x16x16_bf16 v[80:83], v[212:213], v[116:117], v[80:83]
	v_pk_mul_f32 v[88:89], v[88:89], v[220:221]
	v_pk_mul_f32 v[90:91], v[90:91], v[222:223]
	v_mfma_f32_16x16x16_bf16 v[84:87], v[212:213], v[118:119], v[84:87]
	v_pk_mul_f32 v[92:93], v[92:93], v[220:221]
	v_pk_mul_f32 v[94:95], v[94:95], v[222:223]
	v_mfma_f32_16x16x16_bf16 v[88:91], v[214:215], v[116:117], v[88:91]
	v_cvt_pk_bf16_f32 v120, v96, v97
	v_cvt_pk_bf16_f32 v121, v98, v99
	v_mfma_f32_16x16x16_bf16 v[92:95], v[214:215], v[118:119], v[92:95]
	v_cvt_pk_bf16_f32 v122, v104, v105
	v_cvt_pk_bf16_f32 v123, v106, v107
	v_cvt_pk_bf16_f32 v156, v100, v101
	v_cvt_pk_bf16_f32 v157, v102, v103
	v_cvt_pk_bf16_f32 v158, v108, v109
	v_cvt_pk_bf16_f32 v159, v110, v111
	s_waitcnt lgkmcnt(4)
	v_mfma_f32_16x16x32_bf16 a[0:3], v[224:227], v[228:231], a[0:3]
	v_mfma_f32_16x16x32_bf16 a[4:7], v[228:231], v[120:123], a[4:7]
	v_mfma_f32_16x16x32_bf16 a[8:11], v[228:231], v[156:159], a[8:11]
	s_waitcnt lgkmcnt(0)
; template <int DK, bool HG, int MODE>
; __device__ void recur_unit(const Params& p, char* smem, int b, int h, char* img, int nstart, int nstep, int nend) {
;     ...
;     for (int r = 0; r < 4; r++) if (kg * 4 + r > l15) sc[r] = 0.f;
;     bf16x4 pA;
;     {
;       unsigned a = pack2(sc[0], sc[1]), c = pack2(sc[2], sc[3]);
;       pA = bf16x4{(short)(a & 0xffff), (short)(a >> 16), (short)(c & 0xffff), (short)(c >> 16)};
;     }
;     bf16x4 vf[2];
;     f32x4 o[2], oin[2];
;     bf16x8 sbv[2][NKS];
; #pragma unroll
;     for (int vt = 0; vt < 2; vt++) {
;       vf[vt] = *(const bf16x4*)&VT[(w * 32 + vt * 16 + l15) * 20 + kg * 4];
; #pragma unroll
;       for (int st = 0; st < NKS; st++) {
;         unsigned s0 = pack2(S[2 * st][vt][0], S[2 * st][vt][1]), s1 = pack2(S[2 * st][vt][2], S[2 * st][vt][3]);
;         unsigned s2 = pack2(S[2 * st + 1][vt][0], S[2 * st + 1][vt][1]), s3 = pack2(S[2 * st + 1][vt][2], S[2 * st + 1][vt][3]);
;         sbv[vt][st] = bf16x8{(short)(s0 & 0xffff), (short)(s0 >> 16), (short)(s1 & 0xffff), (short)(s1 >> 16),
;                            (short)(s2 & 0xffff), (short)(s2 >> 16), (short)(s3 & 0xffff), (short)(s3 >> 16)};
;       }
;     }
;     STAGE();
; #pragma unroll
;     for (int vt = 0; vt < 2; vt++) {
;       o[vt] = __builtin_amdgcn_mfma_f32_16x16x16bf16_1k(pA, vf[vt], f32x4{0, 0, 0, 0}, 0, 0, 0);
;       oin[vt] = f32x4{0, 0, 0, 0};
; #pragma unroll
;       for (int st = 0; st < NKS; st++) oin[vt] = __builtin_amdgcn_mfma_f32_16x16x32_bf16(qf[st], sbv[vt][st], oin[vt], 0, 0, 0);
;     }
;     STAGE();
;     bf16x4 khf[NKT];
; #pragma unroll
;     for (int kt2 = 0; kt2 < NKT; kt2++) {
;       khf[kt2] = *(const bf16x4*)&KhT[(16 * kt2 + l15) * 20 + kg * 4];
;       float4 g4 = *(const float4*)&Gch[16 * kt2 + kg * 4];
;       f32x4 gv = f32x4{g4.x, g4.y, g4.z, g4.w};
;       S[kt2][0] *= gv; S[kt2][1] *= gv;
;     }
;     STAGE();
; #pragma unroll
;     for (int kt2 = 0; kt2 < NKT; kt2++) {
; #pragma unroll
;       for (int vt = 0; vt < 2; vt++)
;         S[kt2][vt] = __builtin_amdgcn_mfma_f32_16x16x16bf16_1k(khf[kt2], vf[vt], S[kt2][vt], 0, 0, 0);
;     }
;     STAGE();
;     float ss[4];
; #pragma unroll
;     for (int r = 0; r < 4; r++) {
;       o[0][r] += oin[0][r]; o[1][r] += oin[1][r];
;       float s = o[0][r] * o[0][r] + o[1][r] * o[1][r];
;       s = dpp_row_sum(s);
;       ss[r] = s;
;     }
	v_pk_mul_f32 v[96:97], v[96:97], v[236:237]
	v_pk_mul_f32 v[98:99], v[98:99], v[238:239]
	v_pk_mul_f32 v[100:101], v[100:101], v[236:237]
	v_pk_mul_f32 v[102:103], v[102:103], v[238:239]
	v_mfma_f32_16x16x16_bf16 v[96:99], v[232:233], v[116:117], v[96:99]
	v_pk_mul_f32 v[104:105], v[104:105], v[112:113]
	v_pk_mul_f32 v[106:107], v[106:107], v[114:115]
	v_mfma_f32_16x16x16_bf16 v[100:103], v[232:233], v[118:119], v[100:103]
	v_pk_mul_f32 v[108:109], v[108:109], v[112:113]
	v_pk_mul_f32 v[110:111], v[110:111], v[114:115]
	v_mfma_f32_16x16x16_bf16 v[104:107], v[234:235], v[116:117], v[104:107]
	s_nop 1
	v_mfma_f32_16x16x16_bf16 v[108:111], v[234:235], v[118:119], v[108:111]
	ds_read_b128 v[204:207], v147 offset:38912
	ds_read_b128 v[208:211], v147 offset:38976
	ds_read_b128 v[212:215], v147 offset:39040
	ds_read_b128 v[216:219], v147 offset:39104
	v_accvgpr_read_b32 v224, a0
	v_accvgpr_read_b32 v225, a1
	v_accvgpr_read_b32 v226, a2
	v_accvgpr_read_b32 v227, a3
	v_cndmask_b32_e64 v224, v224, 0, s[14:15]
	v_cndmask_b32_e64 v225, v225, 0, s[16:17]
	v_cndmask_b32_e64 v226, v226, 0, s[18:19]
	v_cndmask_b32_e64 v227, v227, 0, s[20:21]
	v_cvt_pk_bf16_f32 v140, v224, v225
	v_cvt_pk_bf16_f32 v141, v226, v227
	s_nop 1
	v_mfma_f32_16x16x16_bf16 v[194:197], v[140:141], v[116:117], 0
	v_mfma_f32_16x16x16_bf16 v[198:201], v[140:141], v[118:119], 0
	v_accvgpr_read_b32 v228, a4
	v_accvgpr_read_b32 v229, a5
	v_accvgpr_read_b32 v230, a6
	v_accvgpr_read_b32 v231, a7
	v_accvgpr_read_b32 v232, a8
	v_accvgpr_read_b32 v233, a9
	v_accvgpr_read_b32 v234, a10
	v_accvgpr_read_b32 v235, a11
	s_nop 1
	v_pk_add_f32 v[194:195], v[194:195], v[228:229]
	v_pk_add_f32 v[196:197], v[196:197], v[230:231]
	v_pk_add_f32 v[198:199], v[198:199], v[232:233]
	v_pk_add_f32 v[200:201], v[200:201], v[234:235]
	v_pk_mul_f32 v[236:237], v[198:199], v[198:199]
	v_pk_mul_f32 v[238:239], v[200:201], v[200:201]
	v_pk_fma_f32 v[112:113], v[194:195], v[194:195], v[236:237]
	v_pk_fma_f32 v[114:115], v[196:197], v[196:197], v[238:239]
	s_nop 1
	v_add_f32_dpp v112, v112, v112 row_ror:8 row_mask:0xf bank_mask:0xf
	v_add_f32_dpp v113, v113, v113 row_ror:8 row_mask:0xf bank_mask:0xf
	v_add_f32_dpp v114, v114, v114 row_ror:8 row_mask:0xf bank_mask:0xf
	v_add_f32_dpp v115, v115, v115 row_ror:8 row_mask:0xf bank_mask:0xf
	v_add_f32_dpp v112, v112, v112 row_ror:4 row_mask:0xf bank_mask:0xf
	v_add_f32_dpp v113, v113, v113 row_ror:4 row_mask:0xf bank_mask:0xf
	v_add_f32_dpp v114, v114, v114 row_ror:4 row_mask:0xf bank_mask:0xf
	v_add_f32_dpp v115, v115, v115 row_ror:4 row_mask:0xf bank_mask:0xf
	v_add_f32_dpp v112, v112, v112 row_ror:2 row_mask:0xf bank_mask:0xf
	v_add_f32_dpp v113, v113, v113 row_ror:2 row_mask:0xf bank_mask:0xf
	v_add_f32_dpp v114, v114, v114 row_ror:2 row_mask:0xf bank_mask:0xf
	v_add_f32_dpp v115, v115, v115 row_ror:2 row_mask:0xf bank_mask:0xf
	v_add_f32_dpp v112, v112, v112 row_ror:1 row_mask:0xf bank_mask:0xf
	v_add_f32_dpp v113, v113, v113 row_ror:1 row_mask:0xf bank_mask:0xf
	v_add_f32_dpp v114, v114, v114 row_ror:1 row_mask:0xf bank_mask:0xf
	v_add_f32_dpp v115, v115, v115 row_ror:1 row_mask:0xf bank_mask:0xf
	s_mov_b64 s[26:27], exec
	s_and_b64 exec, exec, s[22:23]
	ds_write_b128 v148, v[112:115] offset:39168
	s_mov_b64 exec, s[26:27]
	s_waitcnt lgkmcnt(1)
	v_pk_add_f32 v[220:221], v[204:205], v[208:209]
	v_pk_add_f32 v[222:223], v[206:207], v[210:211]
	v_pk_add_f32 v[220:221], v[220:221], v[212:213]
	v_pk_add_f32 v[222:223], v[222:223], v[214:215]
	v_pk_add_f32 v[220:221], v[220:221], v[216:217]
	v_pk_add_f32 v[222:223], v[222:223], v[218:219]
	v_fma_f32 v220, v220, s30, v177
	v_fma_f32 v221, v221, s30, v177
	v_fma_f32 v222, v222, s30, v177
	v_fma_f32 v223, v223, s30, v177
	v_rsq_f32_e32 v220, v220
	v_rsq_f32_e32 v221, v221
	v_rsq_f32_e32 v222, v222
	v_rsq_f32_e32 v223, v223
	s_nop 0
	v_mul_f32_e32 v204, v186, v220
	v_mul_f32_e32 v205, v187, v221
	v_mul_f32_e32 v206, v188, v222
	v_mul_f32_e32 v207, v189, v223
	v_mul_f32_e32 v208, v190, v220
	v_mul_f32_e32 v209, v191, v221
	v_mul_f32_e32 v210, v192, v222
	v_mul_f32_e32 v211, v193, v223
	v_mul_f32_e32 v204, v175, v204
	v_mul_f32_e32 v205, v175, v205
	v_mul_f32_e32 v206, v175, v206
	v_mul_f32_e32 v207, v175, v207
	v_mul_f32_e32 v208, v176, v208
	v_mul_f32_e32 v209, v176, v209
	v_mul_f32_e32 v210, v176, v210
	v_mul_f32_e32 v211, v176, v211
	ds_write_b32 v149, v204 offset:39424
	ds_write_b32 v149, v205 offset:39952
	ds_write_b32 v149, v206 offset:40480
	ds_write_b32 v149, v207 offset:41008
	ds_write_b32 v149, v208 offset:39488
	ds_write_b32 v149, v209 offset:40016
	ds_write_b32 v149, v210 offset:40544
	ds_write_b32 v149, v211 offset:41072
	s_cmp_lg_u32 s29, 0
	s_cbranch_scc1 .Lrec_hg_p1w_d
	s_waitcnt vmcnt(9)
	s_branch .Lrec_hg_p1w_c

; __device__ void phaseB(const Params& p, char* smem) {
;     ...
;     auto cload = [&](int u, float4 (&v)[4]) {
;       const int tile = u & 127, mat = (u >> 7) & 1, e = u >> 8;
;       const float* W = (mat ? p.w_up : p.w_gate) + (size_t)e * DM * DEXP + (size_t)((tile & 15) * 64) * DEXP + (tile >> 4) * 64;
; #pragma unroll
;       for (int i = 0; i < 4; i++) v[i] = *(const float4*)&W[(size_t)(tr + 16 * i) * DEXP + tc4];
;     };
;     auto cproc = [&](int u, float4 (&v)[4]) {
;       const int tile = u & 127, mat = (u >> 7) & 1, e = u >> 8;
;       u16* WT = (mat ? p.WuT : p.WgT) + (size_t)e * DEXP * DM;
;       const int k0 = (tile & 15) * 64, n0 = (tile >> 4) * 64;
;       __syncthreads();
; #pragma unroll
;       for (int i = 0; i < 4; i++) {
;         const int k = tr + 16 * i;
;         T[(tc4 + 0) * 72 + k] = f2bf(v[i].x); T[(tc4 + 1) * 72 + k] = f2bf(v[i].y);
;         T[(tc4 + 2) * 72 + k] = f2bf(v[i].z); T[(tc4 + 3) * 72 + k] = f2bf(v[i].w);
;       }
;       __syncthreads();
;       const int n = threadIdx.x >> 2, seg = (threadIdx.x & 3) * 16;
;       const u32x4 a = *(const u32x4*)&T[n * 72 + seg], b = *(const u32x4*)&T[n * 72 + seg + 8];
;       *(u32x4*)&WT[(size_t)(n0 + n) * DM + k0 + seg] = a;
;       *(u32x4*)&WT[(size_t)(n0 + n) * DM + k0 + seg + 8] = b;
;     };
;     auto conv_range = [&](int u, int uend) -> int {
;       float4 va[4], vb[4];
;       if (u < uend) cload(u, va);
;       while (u < uend) {
;         if (u + nb < uend) cload(u + nb, vb);
;         cproc(u, va);
;         u += nb;
;         if (u >= uend) break;
;         if (u + nb < uend) cload(u + nb, va);
;         cproc(u, vb);
;         u += nb;
;       }
;       return u;
;     };
.LBB0_825:
	v_and_b32_e32 v96, 60, v127
	s_cmpk_gt_i32 s4, 0x1fff
	v_lshlrev_b32_e32 v98, 11, v132
	v_lshlrev_b32_e32 v100, 2, v96
	v_and_b32_e32 v97, 48, v140
	v_lshlrev_b32_e32 v137, 1, v132
	s_cbranch_scc1 .LBB0_836
	s_ashr_i32 s0, s4, 8
	v_readlane_b32 s8, v240, 26
	s_bitcmp0_b32 s4, 7
	v_readlane_b32 s16, v240, 34
	v_readlane_b32 s17, v240, 35
	v_readlane_b32 s18, v240, 36
	v_readlane_b32 s19, v240, 37
	s_cselect_b32 s2, s17, s19
	s_cselect_b32 s3, s16, s18
	s_ashr_i32 s1, s0, 31
	s_lshl_b64 s[0:1], s[0:1], 21
	s_add_u32 s0, s3, s0
	v_readlane_b32 s9, v240, 27
	s_addc_u32 s1, s2, s1
	s_lshl_b32 s2, s40, 17
	s_lshl_b32 s9, s40, 15
	s_and_b32 s2, s2, 0x1e0000
	s_add_u32 s0, s0, s2
	s_addc_u32 s1, s1, 0
	s_lshl_b32 s2, s4, 4
	s_and_b32 s2, s2, 0x700
	s_add_u32 s0, s0, s2
	s_waitcnt vmcnt(2)
	v_mov_b32_e32 v33, 0
	s_addc_u32 s1, s1, 0
	v_mov_b32_e32 v99, v33
	v_add_u32_e32 v34, 0x8000, v98
	v_mov_b32_e32 v35, v33
	s_waitcnt vmcnt(1)
	v_add_u32_e32 v36, 0x10000, v98
	v_mov_b32_e32 v37, v33
	v_add_u32_e32 v38, 0x18000, v98
	v_mov_b32_e32 v39, v33
	s_waitcnt vmcnt(0)
	v_lshl_add_u64 v[0:1], s[0:1], 0, v[98:99]
	v_mov_b32_e32 v101, v33
	v_lshl_add_u64 v[2:3], s[0:1], 0, v[34:35]
	v_lshl_add_u64 v[8:9], s[0:1], 0, v[36:37]
	v_lshl_add_u64 v[10:11], s[0:1], 0, v[38:39]
	v_lshl_add_u64 v[0:1], v[0:1], 0, v[100:101]
	v_lshl_add_u64 v[4:5], v[2:3], 0, v[100:101]
	v_lshl_add_u64 v[8:9], v[8:9], 0, v[100:101]
	v_lshl_add_u64 v[12:13], v[10:11], 0, v[100:101]
	global_load_dwordx4 v[0:3], v[0:1], off
	s_nop 0
	global_load_dwordx4 v[4:7], v[4:5], off
	s_nop 0
	global_load_dwordx4 v[8:11], v[8:9], off
	s_nop 0
	global_load_dwordx4 v[12:15], v[12:13], off
	v_readlane_b32 s14, v240, 32
	s_lshl_b32 s0, s5, 15
	v_readlane_b32 s10, v240, 28
	v_mul_u32_u24_e32 v16, 0x90, v96
	s_add_i32 s14, s0, s9
	s_add_i32 s0, s5, s24
	v_readlane_b32 s11, v240, 29
	v_readlane_b32 s12, v240, 30
	v_readlane_b32 s13, v240, 31
	v_add3_u32 v40, 0, v16, v137
	v_mul_u32_u24_e32 v16, 0x90, v135
	v_lshlrev_b32_e32 v17, 1, v97
	s_lshl_b32 s3, s40, 2
	s_lshl_b32 s6, s24, 3
	s_lshl_b32 s10, s24, 2
	s_add_i32 s0, s0, s40
	v_add3_u32 v41, 0, v16, v17
	s_lshl_b32 s11, s4, 6
	s_lshl_b32 s2, s24, 7
	s_lshl_b32 s12, s5, 2
	s_lshl_b32 s7, s24, 1
	s_lshl_b32 s8, s24, 16
	s_add_i32 s9, s6, s3
	s_add_i32 s10, s10, s3
	s_lshl_b32 s13, s0, 6
	s_lshl_b32 s5, s24, 15
	v_readlane_b32 s15, v240, 33
	v_readlane_b32 s20, v240, 38
	v_readlane_b32 s21, v240, 39
	v_readlane_b32 s22, v240, 40
	v_readlane_b32 s23, v240, 41
	s_branch .LBB0_828
.LBB0_827:
	v_cvt_pk_bf16_f32 v32, v20, s0
	s_barrier
	ds_write_b16 v40, v32
	v_cvt_pk_bf16_f32 v32, v21, s0
	ds_write_b16 v40, v32 offset:144
	v_cvt_pk_bf16_f32 v32, v22, s0
	ds_write_b16 v40, v32 offset:288
	v_cvt_pk_bf16_f32 v32, v23, s0
	ds_write_b16 v40, v32 offset:432
	v_cvt_pk_bf16_f32 v32, v16, s0
	ds_write_b16 v40, v32 offset:32
	v_cvt_pk_bf16_f32 v32, v17, s0
	ds_write_b16 v40, v32 offset:176
	v_cvt_pk_bf16_f32 v32, v18, s0
	ds_write_b16 v40, v32 offset:320
	v_cvt_pk_bf16_f32 v32, v19, s0
	ds_write_b16 v40, v32 offset:464
	v_cvt_pk_bf16_f32 v32, v28, s0
	ds_write_b16 v40, v32 offset:64
	v_cvt_pk_bf16_f32 v32, v29, s0
	ds_write_b16 v40, v32 offset:208
	v_cvt_pk_bf16_f32 v32, v30, s0
	ds_write_b16 v40, v32 offset:352
	v_cvt_pk_bf16_f32 v32, v31, s0
	ds_write_b16 v40, v32 offset:496
	v_cvt_pk_bf16_f32 v32, v24, s0
	s_add_i32 s4, s25, s24
	ds_write_b16 v40, v32 offset:96
	v_cvt_pk_bf16_f32 v32, v25, s0
	s_bitcmp0_b32 s25, 7
	ds_write_b16 v40, v32 offset:240
	v_cvt_pk_bf16_f32 v32, v26, s0
	s_cselect_b32 s14, s75, s77
	s_cselect_b32 s16, s74, s76
	ds_write_b16 v40, v32 offset:384
	v_cvt_pk_bf16_f32 v32, v27, s0
	s_add_i32 s0, s10, s12
	s_and_b32 s17, s0, 0x1c0
	s_ashr_i32 s0, s25, 8
	ds_write_b16 v40, v32 offset:528
	s_ashr_i32 s1, s0, 31
	s_waitcnt lgkmcnt(0)
	s_barrier
	ds_read_b128 v[42:45], v41
	ds_read_b128 v[46:49], v41 offset:16
	s_and_b32 s18, s13, 0x3c0
	s_lshl_b64 s[0:1], s[0:1], 20
	s_add_u32 s0, s16, s0
	v_add_lshl_u32 v32, s17, v135, 10
	s_addc_u32 s1, s14, s1
	v_or3_b32 v32, v32, s18, v97
	s_add_i32 s11, s11, s2
	s_add_i32 s12, s12, s6
	s_add_i32 s13, s13, s2
	v_lshlrev_b32_e32 v32, 1, v32
	s_cmpk_gt_i32 s4, 0x1fff
	s_waitcnt lgkmcnt(1)
	global_store_dwordx4 v32, v[42:45], s[0:1]
	s_waitcnt lgkmcnt(0)
	global_store_dwordx4 v32, v[46:49], s[0:1] offset:16
	s_cselect_b64 s[0:1], -1, 0
	s_mov_b32 s25, s4
	s_mov_b32 s14, s15
	s_and_b64 vcc, exec, s[0:1]
	s_cbranch_vccnz .LBB0_837
; __device__ void phaseB(const Params& p, char* smem) {
;     ...
;     auto cload = [&](int u, float4 (&v)[4]) {
;       const int tile = u & 127, mat = (u >> 7) & 1, e = u >> 8;
;       const float* W = (mat ? p.w_up : p.w_gate) + (size_t)e * DM * DEXP + (size_t)((tile & 15) * 64) * DEXP + (tile >> 4) * 64;
; #pragma unroll
;       for (int i = 0; i < 4; i++) v[i] = *(const float4*)&W[(size_t)(tr + 16 * i) * DEXP + tc4];
;     };
;     auto cproc = [&](int u, float4 (&v)[4]) {
;       const int tile = u & 127, mat = (u >> 7) & 1, e = u >> 8;
;       u16* WT = (mat ? p.WuT : p.WgT) + (size_t)e * DEXP * DM;
;       const int k0 = (tile & 15) * 64, n0 = (tile >> 4) * 64;
;       __syncthreads();
; #pragma unroll
;       for (int i = 0; i < 4; i++) {
;         const int k = tr + 16 * i;
;         T[(tc4 + 0) * 72 + k] = f2bf(v[i].x); T[(tc4 + 1) * 72 + k] = f2bf(v[i].y);
;         T[(tc4 + 2) * 72 + k] = f2bf(v[i].z); T[(tc4 + 3) * 72 + k] = f2bf(v[i].w);
;       }
;       __syncthreads();
;       const int n = threadIdx.x >> 2, seg = (threadIdx.x & 3) * 16;
;       const u32x4 a = *(const u32x4*)&T[n * 72 + seg], b = *(const u32x4*)&T[n * 72 + seg + 8];
;       *(u32x4*)&WT[(size_t)(n0 + n) * DM + k0 + seg] = a;
;       *(u32x4*)&WT[(size_t)(n0 + n) * DM + k0 + seg + 8] = b;
;     };
;     auto conv_range = [&](int u, int uend) -> int {
;       float4 va[4], vb[4];
;       if (u < uend) cload(u, va);
;       while (u < uend) {
;         if (u + nb < uend) cload(u + nb, vb);
;         cproc(u, va);
;         u += nb;
;         if (u >= uend) break;
;         if (u + nb < uend) cload(u + nb, va);
;         cproc(u, vb);
;         u += nb;
;       }
;       return u;
;     };
.LBB0_828:
	s_add_i32 s25, s4, s24
	s_cmpk_lt_i32 s25, 0x2000
	s_cselect_b64 s[0:1], -1, 0
	s_cmpk_gt_i32 s25, 0x1fff
	s_cbranch_scc1 .LBB0_830
	s_ashr_i32 s16, s25, 8
	v_readlane_b32 s36, v240, 26
	s_bitcmp0_b32 s25, 7
	v_readlane_b32 s44, v240, 34
	v_readlane_b32 s45, v240, 35
	v_readlane_b32 s46, v240, 36
	v_readlane_b32 s47, v240, 37
	s_cselect_b32 s15, s45, s47
	s_cselect_b32 s18, s44, s46
	s_ashr_i32 s17, s16, 31
	s_lshl_b64 s[16:17], s[16:17], 21
	s_add_u32 s16, s18, s16
	s_addc_u32 s15, s15, s17
	s_add_i32 s17, s5, s14
	s_and_b32 s17, s17, 0x78000
	s_lshl_b32 s17, s17, 2
	s_add_u32 s16, s16, s17
	s_addc_u32 s15, s15, 0
	s_add_i32 s17, s10, s12
	s_and_b32 s17, s17, 0x1c0
	s_lshl_b32 s17, s17, 2
	s_add_u32 s16, s16, s17
	s_addc_u32 s17, s15, 0
	v_lshl_add_u64 v[16:17], s[16:17], 0, v[98:99]
	v_lshlrev_b32_e32 v32, 2, v96
	v_lshl_add_u64 v[18:19], s[16:17], 0, v[34:35]
	v_lshl_add_u64 v[24:25], s[16:17], 0, v[36:37]
	v_lshl_add_u64 v[26:27], s[16:17], 0, v[38:39]
	v_lshl_add_u64 v[16:17], v[16:17], 0, v[32:33]
	v_lshl_add_u64 v[18:19], v[18:19], 0, v[32:33]
	v_lshl_add_u64 v[24:25], v[24:25], 0, v[32:33]
	v_lshl_add_u64 v[26:27], v[26:27], 0, v[32:33]
	global_load_dwordx4 v[20:23], v[16:17], off
	s_nop 0
	global_load_dwordx4 v[16:19], v[18:19], off
	s_nop 0
	global_load_dwordx4 v[28:31], v[24:25], off
	s_nop 0
	global_load_dwordx4 v[24:27], v[26:27], off
	v_readlane_b32 s37, v240, 27
	v_readlane_b32 s38, v240, 28
	v_readlane_b32 s39, v240, 29
	v_readlane_b32 s40, v240, 30
	v_readlane_b32 s41, v240, 31
	v_readlane_b32 s42, v240, 32
	v_readlane_b32 s43, v240, 33
	v_readlane_b32 s48, v240, 38
	v_readlane_b32 s49, v240, 39
	v_readlane_b32 s50, v240, 40
	v_readlane_b32 s51, v240, 41
.LBB0_830:
	s_waitcnt vmcnt(3)
	v_cvt_pk_bf16_f32 v32, v0, s0
	s_barrier
	ds_write_b16 v40, v32
	v_cvt_pk_bf16_f32 v32, v1, s0
	ds_write_b16 v40, v32 offset:144
	v_cvt_pk_bf16_f32 v32, v2, s0
	ds_write_b16 v40, v32 offset:288
	v_cvt_pk_bf16_f32 v32, v3, s0
	ds_write_b16 v40, v32 offset:432
	s_waitcnt vmcnt(2)
	v_cvt_pk_bf16_f32 v32, v4, s0
	ds_write_b16 v40, v32 offset:32
	v_cvt_pk_bf16_f32 v32, v5, s0
	ds_write_b16 v40, v32 offset:176
	v_cvt_pk_bf16_f32 v32, v6, s0
	ds_write_b16 v40, v32 offset:320
	v_cvt_pk_bf16_f32 v32, v7, s0
	ds_write_b16 v40, v32 offset:464
	s_waitcnt vmcnt(1)
	v_cvt_pk_bf16_f32 v32, v8, s0
	ds_write_b16 v40, v32 offset:64
	v_cvt_pk_bf16_f32 v32, v9, s0
	ds_write_b16 v40, v32 offset:208
	v_cvt_pk_bf16_f32 v32, v10, s0
	ds_write_b16 v40, v32 offset:352
	v_cvt_pk_bf16_f32 v32, v11, s0
	ds_write_b16 v40, v32 offset:496
	s_waitcnt vmcnt(0)
	v_cvt_pk_bf16_f32 v32, v12, s0
	ds_write_b16 v40, v32 offset:96
	v_cvt_pk_bf16_f32 v32, v13, s0
	s_bitcmp0_b32 s4, 7
	ds_write_b16 v40, v32 offset:240
	v_cvt_pk_bf16_f32 v32, v14, s0
	s_cselect_b32 s15, s75, s77
	s_cselect_b32 s18, s74, s76
	ds_write_b16 v40, v32 offset:384
	v_cvt_pk_bf16_f32 v32, v15, s0
	s_add_i32 s16, s3, s12
	ds_write_b16 v40, v32 offset:528
	s_and_b32 s19, s16, 0x1c0
	s_ashr_i32 s16, s4, 8
	s_waitcnt lgkmcnt(0)
	s_barrier
	ds_read_b128 v[42:45], v41
	ds_read_b128 v[46:49], v41 offset:16
	s_ashr_i32 s17, s16, 31
	s_and_b32 s20, s11, 0x3c0
	s_lshl_b64 s[16:17], s[16:17], 20
	v_add_lshl_u32 v32, s19, v135, 10
	s_add_u32 s16, s18, s16
	v_or3_b32 v32, v32, s20, v97
	s_addc_u32 s17, s15, s17
	v_lshlrev_b32_e32 v32, 1, v32
	s_andn2_b64 vcc, exec, s[0:1]
	s_mov_b64 s[0:1], -1
	s_waitcnt lgkmcnt(1)
	global_store_dwordx4 v32, v[42:45], s[16:17]
	s_waitcnt lgkmcnt(0)
	global_store_dwordx4 v32, v[46:49], s[16:17] offset:16
	s_cbranch_vccnz .LBB0_835
	s_add_i32 s4, s7, s4
	s_cmpk_lt_i32 s4, 0x2000
	s_cbranch_scc1 .LBB0_833
	s_add_i32 s15, s14, s8
	s_mov_b64 s[0:1], 0

; __device__ void phaseB(const Params& p, char* smem) {
;     ...
;     auto cload = [&](int u, float4 (&v)[4]) {
;       const int tile = u & 127, mat = (u >> 7) & 1, e = u >> 8;
;       const float* W = (mat ? p.w_up : p.w_gate) + (size_t)e * DM * DEXP + (size_t)((tile & 15) * 64) * DEXP + (tile >> 4) * 64;
; #pragma unroll
;       for (int i = 0; i < 4; i++) v[i] = *(const float4*)&W[(size_t)(tr + 16 * i) * DEXP + tc4];
;     };
;     auto cproc = [&](int u, float4 (&v)[4]) {
;       const int tile = u & 127, mat = (u >> 7) & 1, e = u >> 8;
;       u16* WT = (mat ? p.WuT : p.WgT) + (size_t)e * DEXP * DM;
;       const int k0 = (tile & 15) * 64, n0 = (tile >> 4) * 64;
;       __syncthreads();
; #pragma unroll
;       for (int i = 0; i < 4; i++) {
;         const int k = tr + 16 * i;
;         T[(tc4 + 0) * 72 + k] = f2bf(v[i].x); T[(tc4 + 1) * 72 + k] = f2bf(v[i].y);
;         T[(tc4 + 2) * 72 + k] = f2bf(v[i].z); T[(tc4 + 3) * 72 + k] = f2bf(v[i].w);
;       }
;       __syncthreads();
;       const int n = threadIdx.x >> 2, seg = (threadIdx.x & 3) * 16;
;       const u32x4 a = *(const u32x4*)&T[n * 72 + seg], b = *(const u32x4*)&T[n * 72 + seg + 8];
;       *(u32x4*)&WT[(size_t)(n0 + n) * DM + k0 + seg] = a;
;       *(u32x4*)&WT[(size_t)(n0 + n) * DM + k0 + seg + 8] = b;
;     };
;     auto conv_range = [&](int u, int uend) -> int {
;       float4 va[4], vb[4];
;       if (u < uend) cload(u, va);
;       while (u < uend) {
;         if (u + nb < uend) cload(u + nb, vb);
;         cproc(u, va);
;         u += nb;
;         if (u >= uend) break;
;         if (u + nb < uend) cload(u + nb, va);
;         cproc(u, vb);
;         u += nb;
;       }
;       return u;
;     };
;     ...
;     conv_range(u, NCV);
.LBB0_905:
	s_cmpk_gt_u32 s25, 0x2fff
	s_cbranch_scc1 .LBB0_916
	v_readlane_b32 s0, v240, 26
	s_bitcmp0_b32 s25, 7
	v_readlane_b32 s1, v240, 27
	v_readlane_b32 s2, v240, 28
	v_readlane_b32 s8, v240, 34
	v_readlane_b32 s9, v240, 35
	v_readlane_b32 s10, v240, 36
	v_readlane_b32 s11, v240, 37
	s_cselect_b32 s0, s9, s11
	s_cselect_b32 s1, s8, s10
	s_lshl_b32 s2, s25, 13
	s_and_b32 s2, s2, 0x7e00000
	s_add_u32 s1, s1, s2
	s_addc_u32 s0, s0, 0
	s_lshl_b32 s2, s25, 17
	s_lshl_b32 s11, s25, 15
	s_and_b32 s2, s2, 0x1e0000
	v_readlane_b32 s3, v240, 29
	s_add_u32 s1, s1, s2
	s_addc_u32 s3, s0, 0
	s_lshl_b32 s0, s25, 4
	s_lshl_b32 s2, s25, 2
	s_and_b32 s0, s0, 0x700
	s_add_u32 s0, s1, s0
	v_mov_b32_e32 v101, 0
	s_addc_u32 s1, s3, 0
	v_mov_b32_e32 v99, v101
	v_add_u32_e32 v32, 0x8000, v98
	v_mov_b32_e32 v33, v101
	v_add_u32_e32 v34, 0x10000, v98
	v_mov_b32_e32 v35, v101
	v_add_u32_e32 v36, 0x18000, v98
	v_mov_b32_e32 v37, v101
	v_lshl_add_u64 v[0:1], s[0:1], 0, v[98:99]
	v_lshl_add_u64 v[2:3], s[0:1], 0, v[32:33]
	v_lshl_add_u64 v[8:9], s[0:1], 0, v[34:35]
	v_lshl_add_u64 v[10:11], s[0:1], 0, v[36:37]
	v_lshl_add_u64 v[0:1], v[0:1], 0, v[100:101]
	v_lshl_add_u64 v[4:5], v[2:3], 0, v[100:101]
	v_lshl_add_u64 v[8:9], v[8:9], 0, v[100:101]
	v_lshl_add_u64 v[12:13], v[10:11], 0, v[100:101]
	global_load_dwordx4 v[0:3], v[0:1], off
	s_nop 0
	global_load_dwordx4 v[4:7], v[4:5], off
	s_nop 0
	global_load_dwordx4 v[8:11], v[8:9], off
	s_nop 0
	global_load_dwordx4 v[12:15], v[12:13], off
	v_mul_u32_u24_e32 v16, 0x90, v96
	v_readlane_b32 s4, v240, 30
	v_readlane_b32 s5, v240, 31
	v_readlane_b32 s6, v240, 32
	v_readlane_b32 s7, v240, 33
	v_add3_u32 v38, 0, v16, v137
	v_mul_u32_u24_e32 v16, 0x90, v135
	v_lshlrev_b32_e32 v17, 1, v97
	v_add3_u32 v39, 0, v16, v17
	s_lshl_b32 s3, s25, 6
	s_lshl_b32 s4, s24, 7
	s_lshl_b32 s5, s24, 3
	s_lshl_b32 s6, s24, 1
	s_lshl_b32 s7, s24, 16
	s_lshl_b32 s8, s24, 2
	s_lshl_b32 s9, s24, 6
	s_lshl_b32 s10, s24, 15
	v_readlane_b32 s12, v240, 38
	v_readlane_b32 s13, v240, 39
	v_readlane_b32 s14, v240, 40
	v_readlane_b32 s15, v240, 41
	s_branch .LBB0_909
.LBB0_907:
	v_cvt_pk_bf16_f32 v40, v20, s0
	s_barrier
	ds_write_b16 v38, v40
	v_cvt_pk_bf16_f32 v40, v21, s0
	ds_write_b16 v38, v40 offset:144
	v_cvt_pk_bf16_f32 v40, v22, s0
	ds_write_b16 v38, v40 offset:288
	v_cvt_pk_bf16_f32 v40, v23, s0
	ds_write_b16 v38, v40 offset:432
	v_cvt_pk_bf16_f32 v40, v16, s0
	ds_write_b16 v38, v40 offset:32
	v_cvt_pk_bf16_f32 v40, v17, s0
	ds_write_b16 v38, v40 offset:176
	v_cvt_pk_bf16_f32 v40, v18, s0
	ds_write_b16 v38, v40 offset:320
	v_cvt_pk_bf16_f32 v40, v19, s0
	ds_write_b16 v38, v40 offset:464
	v_cvt_pk_bf16_f32 v40, v28, s0
	ds_write_b16 v38, v40 offset:64
	v_cvt_pk_bf16_f32 v40, v29, s0
	ds_write_b16 v38, v40 offset:208
	v_cvt_pk_bf16_f32 v40, v30, s0
	ds_write_b16 v38, v40 offset:352
	v_cvt_pk_bf16_f32 v40, v31, s0
	ds_write_b16 v38, v40 offset:496
	v_cvt_pk_bf16_f32 v40, v24, s0
	s_add_i32 s25, s12, s24
	ds_write_b16 v38, v40 offset:96
	v_cvt_pk_bf16_f32 v40, v25, s0
	s_bitcmp0_b32 s12, 7
	ds_write_b16 v38, v40 offset:240
	v_cvt_pk_bf16_f32 v40, v26, s0
	s_cselect_b32 s11, s75, s77
	s_cselect_b32 s15, s74, s76
	ds_write_b16 v38, v40 offset:384
	v_cvt_pk_bf16_f32 v40, v27, s0
	s_add_i32 s0, s8, s2
	s_and_b32 s2, s0, 0x1c0
	s_add_i32 s0, s9, s3
	s_and_b32 s16, s0, 0x3c0
	s_ashr_i32 s0, s12, 8
	ds_write_b16 v38, v40 offset:528
	s_ashr_i32 s1, s0, 31
	s_waitcnt lgkmcnt(0)
	s_barrier
	ds_read_b128 v[40:43], v39
	ds_read_b128 v[44:47], v39 offset:16
	s_lshl_b64 s[0:1], s[0:1], 20
	s_add_u32 s0, s15, s0
	v_add_lshl_u32 v48, s2, v135, 10
	s_addc_u32 s1, s11, s1
	v_or3_b32 v48, v48, s16, v97
	s_add_i32 s3, s3, s4
	v_lshlrev_b32_e32 v48, 1, v48
	s_cmpk_gt_i32 s25, 0x2fff
	s_waitcnt lgkmcnt(1)
	global_store_dwordx4 v48, v[40:43], s[0:1]
	s_waitcnt lgkmcnt(0)
	global_store_dwordx4 v48, v[44:47], s[0:1] offset:16
	s_cselect_b64 s[0:1], -1, 0
	s_mov_b32 s2, s14
	s_mov_b32 s11, s13

; __device__ void phaseB(const Params& p, char* smem) {
;     ...
;     auto cload = [&](int u, float4 (&v)[4]) {
;       const int tile = u & 127, mat = (u >> 7) & 1, e = u >> 8;
;       const float* W = (mat ? p.w_up : p.w_gate) + (size_t)e * DM * DEXP + (size_t)((tile & 15) * 64) * DEXP + (tile >> 4) * 64;
; #pragma unroll
;       for (int i = 0; i < 4; i++) v[i] = *(const float4*)&W[(size_t)(tr + 16 * i) * DEXP + tc4];
;     };
;     auto cproc = [&](int u, float4 (&v)[4]) {
;       const int tile = u & 127, mat = (u >> 7) & 1, e = u >> 8;
;       u16* WT = (mat ? p.WuT : p.WgT) + (size_t)e * DEXP * DM;
;       const int k0 = (tile & 15) * 64, n0 = (tile >> 4) * 64;
;       __syncthreads();
; #pragma unroll
;       for (int i = 0; i < 4; i++) {
;         const int k = tr + 16 * i;
;         T[(tc4 + 0) * 72 + k] = f2bf(v[i].x); T[(tc4 + 1) * 72 + k] = f2bf(v[i].y);
;         T[(tc4 + 2) * 72 + k] = f2bf(v[i].z); T[(tc4 + 3) * 72 + k] = f2bf(v[i].w);
;       }
;       __syncthreads();
;       const int n = threadIdx.x >> 2, seg = (threadIdx.x & 3) * 16;
;       const u32x4 a = *(const u32x4*)&T[n * 72 + seg], b = *(const u32x4*)&T[n * 72 + seg + 8];
;       *(u32x4*)&WT[(size_t)(n0 + n) * DM + k0 + seg] = a;
;       *(u32x4*)&WT[(size_t)(n0 + n) * DM + k0 + seg + 8] = b;
;     };
;     auto conv_range = [&](int u, int uend) -> int {
;       float4 va[4], vb[4];
;       if (u < uend) cload(u, va);
;       while (u < uend) {
;         if (u + nb < uend) cload(u + nb, vb);
;         cproc(u, va);
;         u += nb;
;         if (u >= uend) break;
;         if (u + nb < uend) cload(u + nb, va);
;         cproc(u, vb);
;         u += nb;
;       }
;       return u;
;     };
.LBB0_909:
	s_add_i32 s12, s25, s24
	s_cmpk_lt_i32 s12, 0x3000
	s_cselect_b64 s[0:1], -1, 0
	s_cmpk_gt_i32 s12, 0x2fff
	s_cbranch_scc1 .LBB0_911
	s_ashr_i32 s14, s12, 8
	v_readlane_b32 s36, v240, 26
	s_bitcmp0_b32 s12, 7
	v_readlane_b32 s44, v240, 34
	v_readlane_b32 s45, v240, 35
	v_readlane_b32 s46, v240, 36
	v_readlane_b32 s47, v240, 37
	s_cselect_b32 s13, s45, s47
	s_cselect_b32 s16, s44, s46
	s_ashr_i32 s15, s14, 31
	s_lshl_b64 s[14:15], s[14:15], 21
	s_add_u32 s14, s16, s14
	s_addc_u32 s13, s13, s15
	s_add_i32 s15, s10, s11
	s_and_b32 s15, s15, 0x78000
	s_lshl_b32 s15, s15, 2
	s_add_u32 s14, s14, s15
	s_addc_u32 s13, s13, 0
	s_add_i32 s15, s8, s2
	s_and_b32 s15, s15, 0x1c0
	s_lshl_b32 s15, s15, 2
	s_add_u32 s14, s14, s15
	s_addc_u32 s15, s13, 0
	v_lshl_add_u64 v[16:17], s[14:15], 0, v[98:99]
	v_lshlrev_b32_e32 v100, 2, v96
	v_lshl_add_u64 v[18:19], s[14:15], 0, v[32:33]
	v_lshl_add_u64 v[24:25], s[14:15], 0, v[34:35]
	v_lshl_add_u64 v[26:27], s[14:15], 0, v[36:37]
	v_lshl_add_u64 v[16:17], v[16:17], 0, v[100:101]
	v_lshl_add_u64 v[18:19], v[18:19], 0, v[100:101]
	v_lshl_add_u64 v[24:25], v[24:25], 0, v[100:101]
	v_lshl_add_u64 v[26:27], v[26:27], 0, v[100:101]
	global_load_dwordx4 v[20:23], v[16:17], off
	s_nop 0
	global_load_dwordx4 v[16:19], v[18:19], off
	s_nop 0
	global_load_dwordx4 v[28:31], v[24:25], off
	s_nop 0
	global_load_dwordx4 v[24:27], v[26:27], off
	v_readlane_b32 s37, v240, 27
	v_readlane_b32 s38, v240, 28
	v_readlane_b32 s39, v240, 29
	v_readlane_b32 s40, v240, 30
	v_readlane_b32 s41, v240, 31
	v_readlane_b32 s42, v240, 32
	v_readlane_b32 s43, v240, 33
	v_readlane_b32 s48, v240, 38
	v_readlane_b32 s49, v240, 39
	v_readlane_b32 s50, v240, 40
	v_readlane_b32 s51, v240, 41
.LBB0_911:
	s_waitcnt vmcnt(3)
	v_cvt_pk_bf16_f32 v40, v0, s0
	s_barrier
	ds_write_b16 v38, v40
	v_cvt_pk_bf16_f32 v40, v1, s0
	ds_write_b16 v38, v40 offset:144
	v_cvt_pk_bf16_f32 v40, v2, s0
	ds_write_b16 v38, v40 offset:288
	v_cvt_pk_bf16_f32 v40, v3, s0
	ds_write_b16 v38, v40 offset:432
	s_waitcnt vmcnt(2)
	v_cvt_pk_bf16_f32 v40, v4, s0
	ds_write_b16 v38, v40 offset:32
	v_cvt_pk_bf16_f32 v40, v5, s0
	ds_write_b16 v38, v40 offset:176
	v_cvt_pk_bf16_f32 v40, v6, s0
	ds_write_b16 v38, v40 offset:320
	v_cvt_pk_bf16_f32 v40, v7, s0
	ds_write_b16 v38, v40 offset:464
	s_waitcnt vmcnt(1)
	v_cvt_pk_bf16_f32 v40, v8, s0
	ds_write_b16 v38, v40 offset:64
	v_cvt_pk_bf16_f32 v40, v9, s0
	ds_write_b16 v38, v40 offset:208
	v_cvt_pk_bf16_f32 v40, v10, s0
	ds_write_b16 v38, v40 offset:352
	v_cvt_pk_bf16_f32 v40, v11, s0
	ds_write_b16 v38, v40 offset:496
	s_waitcnt vmcnt(0)
	v_cvt_pk_bf16_f32 v40, v12, s0
	ds_write_b16 v38, v40 offset:96
	v_cvt_pk_bf16_f32 v40, v13, s0
	ds_write_b16 v38, v40 offset:240
	v_cvt_pk_bf16_f32 v40, v14, s0
	s_bitcmp0_b32 s25, 7
	ds_write_b16 v38, v40 offset:384
	v_cvt_pk_bf16_f32 v40, v15, s0
	s_cselect_b32 s13, s75, s77
	s_cselect_b32 s16, s74, s76
	ds_write_b16 v38, v40 offset:528
	s_ashr_i32 s14, s25, 8
	s_waitcnt lgkmcnt(0)
	s_barrier
	ds_read_b128 v[40:43], v39
	ds_read_b128 v[44:47], v39 offset:16
	s_and_b32 s17, s2, 0x1c0
	s_ashr_i32 s15, s14, 31
	s_and_b32 s18, s3, 0x3c0
	s_lshl_b64 s[14:15], s[14:15], 20
	v_add_lshl_u32 v48, s17, v135, 10
	s_add_u32 s14, s16, s14
	v_or3_b32 v48, v48, s18, v97
	s_addc_u32 s15, s13, s15
	v_lshlrev_b32_e32 v48, 1, v48
	s_andn2_b64 vcc, exec, s[0:1]
	s_mov_b64 s[0:1], -1
	s_waitcnt lgkmcnt(1)
	global_store_dwordx4 v48, v[40:43], s[14:15]
	s_waitcnt lgkmcnt(0)
	global_store_dwordx4 v48, v[44:47], s[14:15] offset:16
	s_cbranch_vccnz .LBB0_908
	s_add_i32 s15, s6, s25
	s_cmpk_lt_i32 s15, 0x3000
	s_cbranch_scc1 .LBB0_914
	s_add_i32 s14, s2, s5
	s_add_i32 s13, s11, s7
	s_mov_b64 s[0:1], 0

; __device__ void phaseB(const Params& p, char* smem) {
;     ...
;     auto cload = [&](int u, float4 (&v)[4]) {
;       const int tile = u & 127, mat = (u >> 7) & 1, e = u >> 8;
;       const float* W = (mat ? p.w_up : p.w_gate) + (size_t)e * DM * DEXP + (size_t)((tile & 15) * 64) * DEXP + (tile >> 4) * 64;
; #pragma unroll
;       for (int i = 0; i < 4; i++) v[i] = *(const float4*)&W[(size_t)(tr + 16 * i) * DEXP + tc4];
;     };
;     auto cproc = [&](int u, float4 (&v)[4]) {
;       const int tile = u & 127, mat = (u >> 7) & 1, e = u >> 8;
;       u16* WT = (mat ? p.WuT : p.WgT) + (size_t)e * DEXP * DM;
;       const int k0 = (tile & 15) * 64, n0 = (tile >> 4) * 64;
;       __syncthreads();
; #pragma unroll
;       for (int i = 0; i < 4; i++) {
;         const int k = tr + 16 * i;
;         T[(tc4 + 0) * 72 + k] = f2bf(v[i].x); T[(tc4 + 1) * 72 + k] = f2bf(v[i].y);
;         T[(tc4 + 2) * 72 + k] = f2bf(v[i].z); T[(tc4 + 3) * 72 + k] = f2bf(v[i].w);
;       }
;       __syncthreads();
;       const int n = threadIdx.x >> 2, seg = (threadIdx.x & 3) * 16;
;       const u32x4 a = *(const u32x4*)&T[n * 72 + seg], b = *(const u32x4*)&T[n * 72 + seg + 8];
;       *(u32x4*)&WT[(size_t)(n0 + n) * DM + k0 + seg] = a;
;       *(u32x4*)&WT[(size_t)(n0 + n) * DM + k0 + seg + 8] = b;
;     };
.LBB0_1109:
	s_mov_b64 exec, -1
	v_readlane_b32 s8, v240, 34
	v_readlane_b32 s9, v240, 35
	v_readlane_b32 s10, v240, 36
	v_readlane_b32 s11, v240, 37
	s_add_u32 s14, s82, 0x3640
	s_addc_u32 s15, s83, 0
	v_and_b32_e32 v0, 63, v128
	v_and_b32_e32 v1, 15, v0
	v_lshrrev_b32_e32 v2, 4, v0
	v_lshlrev_b32_e32 v3, 13, v1
	v_lshl_add_u32 v3, v2, 4, v3
	v_add_u32_e32 v4, 0x1000, v3
	v_lshlrev_b32_e32 v5, 13, v2
	v_lshl_add_u32 v5, v1, 3, v5
	v_add_u32_e32 v74, 0x0, v5
	v_add_u32_e32 v75, 0x1000, v5
	v_add_u32_e32 v76, 0x8000, v5
	v_add_u32_e32 v77, 0x9000, v5
	v_add_u32_e32 v78, 0x10000, v5
	v_add_u32_e32 v79, 0x11000, v5
	v_add_u32_e32 v80, 0x18000, v5
	v_add_u32_e32 v81, 0x19000, v5
	v_mov_b32_e32 v7, 1
	v_mov_b32_e32 v8, 0
	v_readlane_b32 s16, v240, 42
	v_lshrrev_b32_e32 v9, 6, v128
	s_nop 0
	v_readfirstlane_b32 s12, v9
	s_nop 3
	s_lshl_b32 s16, s16, 2
	s_add_u32 s16, s16, s12
	s_mov_b32 s13, s16
	s_branch .Lcvc_first
.Lcvc_next:
	s_add_u32 s13, s13, 2048
	s_mov_b32 s16, s13
.Lcvc_first:
	s_cmp_ge_u32 s16, 4096
	s_cbranch_scc1 .Lcvc_done
	s_add_u32 s16, s16, 12288
	s_and_b32 s17, s16, 127
	s_lshr_b32 s18, s16, 8
	s_bitcmp1_b32 s16, 7
	s_cselect_b32 s20, s10, s8
	s_cselect_b32 s21, s11, s9
	s_cselect_b32 s22, s76, s74
	s_cselect_b32 s23, s77, s75
	s_and_b32 s19, s17, 15
	s_lshr_b32 s17, s17, 4
	s_lshl_b32 s24, s18, 21
	s_add_u32 s20, s20, s24
	s_addc_u32 s21, s21, 0
	s_lshl_b32 s24, s19, 17
	s_lshl_b32 s25, s17, 8
	s_add_u32 s24, s24, s25
	s_add_u32 s20, s20, s24
	s_addc_u32 s21, s21, 0
	s_lshl_b32 s24, s18, 20
	s_add_u32 s22, s22, s24
	s_addc_u32 s23, s23, 0
	s_lshl_b32 s24, s17, 17
	s_lshl_b32 s25, s19, 7
	s_add_u32 s24, s24, s25
	s_add_u32 s22, s22, s24
	s_addc_u32 s23, s23, 0
	global_load_dwordx4 v[10:13], v3, s[20:21] offset:0
	global_load_dwordx4 v[14:17], v3, s[20:21] offset:2048
	global_load_dwordx4 v[18:21], v4, s[20:21] offset:0
	global_load_dwordx4 v[22:25], v4, s[20:21] offset:2048
	global_load_dwordx4 v[26:29], v3, s[20:21] offset:64
	global_load_dwordx4 v[30:33], v3, s[20:21] offset:2112
	global_load_dwordx4 v[34:37], v4, s[20:21] offset:64
	global_load_dwordx4 v[38:41], v4, s[20:21] offset:2112
	global_load_dwordx4 v[42:45], v3, s[20:21] offset:128
	global_load_dwordx4 v[46:49], v3, s[20:21] offset:2176
	global_load_dwordx4 v[50:53], v4, s[20:21] offset:128
	global_load_dwordx4 v[54:57], v4, s[20:21] offset:2176
	global_load_dwordx4 v[58:61], v3, s[20:21] offset:192
	global_load_dwordx4 v[62:65], v3, s[20:21] offset:2240
	global_load_dwordx4 v[66:69], v4, s[20:21] offset:192
	global_load_dwordx4 v[70:73], v4, s[20:21] offset:2240
	s_waitcnt vmcnt(12)
	v_cvt_pk_bf16_f32 v82, v10, v14
	v_cvt_pk_bf16_f32 v83, v18, v22
	v_cvt_pk_bf16_f32 v84, v11, v15
	v_cvt_pk_bf16_f32 v85, v19, v23
	v_cvt_pk_bf16_f32 v86, v12, v16
	v_cvt_pk_bf16_f32 v87, v20, v24
	v_cvt_pk_bf16_f32 v88, v13, v17
	v_cvt_pk_bf16_f32 v89, v21, v25
	global_store_dwordx2 v74, v[82:83], s[22:23]
	global_store_dwordx2 v74, v[84:85], s[22:23] offset:2048
	global_store_dwordx2 v75, v[86:87], s[22:23]
	global_store_dwordx2 v75, v[88:89], s[22:23] offset:2048
	s_waitcnt vmcnt(12)
	v_cvt_pk_bf16_f32 v82, v26, v30
	v_cvt_pk_bf16_f32 v83, v34, v38
	v_cvt_pk_bf16_f32 v84, v27, v31
	v_cvt_pk_bf16_f32 v85, v35, v39
	v_cvt_pk_bf16_f32 v86, v28, v32
	v_cvt_pk_bf16_f32 v87, v36, v40
	v_cvt_pk_bf16_f32 v88, v29, v33
	v_cvt_pk_bf16_f32 v89, v37, v41
	global_store_dwordx2 v76, v[82:83], s[22:23]
	global_store_dwordx2 v76, v[84:85], s[22:23] offset:2048
	global_store_dwordx2 v77, v[86:87], s[22:23]
	global_store_dwordx2 v77, v[88:89], s[22:23] offset:2048
	s_waitcnt vmcnt(12)
	v_cvt_pk_bf16_f32 v82, v42, v46
	v_cvt_pk_bf16_f32 v83, v50, v54
	v_cvt_pk_bf16_f32 v84, v43, v47
	v_cvt_pk_bf16_f32 v85, v51, v55
	v_cvt_pk_bf16_f32 v86, v44, v48
	v_cvt_pk_bf16_f32 v87, v52, v56
	v_cvt_pk_bf16_f32 v88, v45, v49
	v_cvt_pk_bf16_f32 v89, v53, v57
	global_store_dwordx2 v78, v[82:83], s[22:23]
	global_store_dwordx2 v78, v[84:85], s[22:23] offset:2048
	global_store_dwordx2 v79, v[86:87], s[22:23]
	global_store_dwordx2 v79, v[88:89], s[22:23] offset:2048
	s_waitcnt vmcnt(12)
	v_cvt_pk_bf16_f32 v82, v58, v62
	v_cvt_pk_bf16_f32 v83, v66, v70
	v_cvt_pk_bf16_f32 v84, v59, v63
	v_cvt_pk_bf16_f32 v85, v67, v71
	v_cvt_pk_bf16_f32 v86, v60, v64
	v_cvt_pk_bf16_f32 v87, v68, v72
	v_cvt_pk_bf16_f32 v88, v61, v65
	v_cvt_pk_bf16_f32 v89, v69, v73
	global_store_dwordx2 v80, v[82:83], s[22:23]
	global_store_dwordx2 v80, v[84:85], s[22:23] offset:2048
	global_store_dwordx2 v81, v[86:87], s[22:23]
	global_store_dwordx2 v81, v[88:89], s[22:23] offset:2048
	s_branch .Lcvc_next
